# strategy: one static s_setprio 1 for waves 4-7 at entry, all per-segment K-loop s_setprio removed
# baseline (speedup 1.0000x reference)
; #define LAS __attribute__((address_space(3)))
; __global__ void __launch_bounds__(NTHR, 2) fwd_kernel(Args args) {
;     extern __shared__ __attribute__((aligned(16))) unsigned char lds_raw[];
;     Frame F;
;     F.lds = (LAS unsigned char*)lds_raw;
;     F.tid = threadIdx.x; F.lane = F.tid & 63; F.wave = __builtin_amdgcn_readfirstlane(F.tid >> 6);
;     F.G = gridDim.x; F.bid = blockIdx.x;
;     F.out = args.out; F.ws = args.ws;
;     volatile LAS unsigned* MISC = (volatile LAS unsigned*)(F.lds + MISC_OFF);
;     if (F.tid < 32) MISC[F.tid] = 0u;
;     __syncthreads();
;     unsigned* ctl = (unsigned*)(F.ws + WS_CTL);
;     ...
;     XcdBarrier bar; bar.bar = ctl + CW_BAR; bar.x = 0; bar.st = nullptr;
;     ...
;     XcdBarrier bar = xcd_barrier_post(ctl + CW_BAR, MISC + 8);
_Z10fwd_kernel4Args:
	s_load_dwordx8 s[84:91], s[0:1], 0xc0
	s_load_dwordx2 s[82:83], s[0:1], 0xe0
	s_load_dword s33, s[0:1], 0xe8
	s_mov_b32 s80, s2
	v_readfirstlane_b32 s98, v0
	s_nop 3
	s_lshr_b32 s98, s98, 6
	s_cmp_ge_u32 s98, 4
	s_cbranch_scc0 .Lstatic_prio_done
	s_setprio 1
.Lstatic_prio_done:
	s_add_u32 s2, s0, 0xe8
	s_addc_u32 s3, s1, 0
	v_cmp_gt_u32_e32 vcc, 32, v0
	v_writelane_b32 v250, s2, 0
	s_nop 1
	v_writelane_b32 v250, s3, 1
	s_and_saveexec_b64 s[2:3], vcc
	v_lshl_add_u32 v1, v0, 2, 0
	v_add_u32_e32 v1, 0x23f00, v1
	v_mov_b32_e32 v2, 0
	ds_write_b32 v1, v2
	s_or_b64 exec, exec, s[2:3]
	s_load_dwordx16 s[4:19], s[0:1], 0x0
	s_load_dwordx16 s[56:71], s[0:1], 0x80
	s_waitcnt lgkmcnt(0)
	s_barrier
	v_writelane_b32 v250, s4, 2
	s_add_u32 s72, s90, 0x4000
	s_addc_u32 s73, s91, 0
	v_writelane_b32 v250, s5, 3
	v_writelane_b32 v250, s6, 4
	v_writelane_b32 v250, s7, 5
	v_writelane_b32 v250, s8, 6
	v_writelane_b32 v250, s9, 7
	v_writelane_b32 v250, s10, 8
	v_writelane_b32 v250, s11, 9
	v_writelane_b32 v250, s12, 10
	v_writelane_b32 v250, s13, 11
	v_writelane_b32 v250, s14, 12
	v_writelane_b32 v250, s15, 13
	v_writelane_b32 v250, s16, 14
	v_writelane_b32 v250, s17, 15
	v_writelane_b32 v250, s18, 16
	v_writelane_b32 v250, s19, 17
	s_load_dwordx16 s[4:19], s[0:1], 0x40
	s_getreg_b32 s0, hwreg(HW_REG_XCC_ID, 0, 4)
	s_and_b32 s74, s0, 15
	v_cmp_eq_u32_e64 s[92:93], 0, v0
	s_waitcnt lgkmcnt(0)
	v_writelane_b32 v250, s4, 18
	s_nop 1
	v_writelane_b32 v250, s5, 19
	v_writelane_b32 v250, s6, 20
	v_writelane_b32 v250, s7, 21
	v_writelane_b32 v250, s8, 22
	v_writelane_b32 v250, s9, 23
	v_writelane_b32 v250, s10, 24
	v_writelane_b32 v250, s11, 25
	v_writelane_b32 v250, s12, 26
	v_writelane_b32 v250, s13, 27
	v_writelane_b32 v250, s14, 28
	v_writelane_b32 v250, s15, 29
	v_writelane_b32 v250, s16, 30
	v_writelane_b32 v250, s17, 31
	v_writelane_b32 v250, s18, 32
	v_writelane_b32 v250, s19, 33
	s_and_saveexec_b64 s[0:1], s[92:93]
	s_cbranch_execz .LBB0_5
	s_mov_b64 s[4:5], exec
	v_mbcnt_lo_u32_b32 v1, s4, 0
	v_mbcnt_hi_u32_b32 v1, s5, v1
	v_cmp_eq_u32_e32 vcc, 0, v1
	s_and_b64 s[6:7], exec, vcc
	s_mov_b64 exec, s[6:7]
	s_cbranch_execz .LBB0_5
	s_lshl_b32 s6, s74, 8
	s_bcnt1_i32_b64 s4, s[4:5]
	v_mov_b32_e32 v1, s6
	v_mov_b32_e32 v2, s4
	global_atomic_add v1, v2, s[72:73] offset:1024

; #define PG8_STAGE(bufoff, gbase, voff) do { _Pragma("unroll") for (int _i = 0; _i < 2; ++_i) \
;         __builtin_amdgcn_global_load_lds((const unsigned*)((const char*)(gbase) + (voff)[_i]), (PG8_LAS unsigned*)(lds + (bufoff) + ldsw + _i * 8192), 16, 0, PG8_AUX_##voff); } while (0)
; #define PG8_LDA(dst, b, h) do { _Pragma("unroll") for (int m = 0; m < 4; ++m) _Pragma("unroll") for (int k = 0; k < 2; ++k) dst[m][k] = *(const PG8_LAS bf16x8*)(lds + PG8_SA(b, h) + aoff + m * 2048 + k * 1024); } while (0)
; #define PG8_LDB(dst, b, h) do { _Pragma("unroll") for (int n = 0; n < 2; ++n) _Pragma("unroll") for (int k = 0; k < 2; ++k) dst[n][k] = *(const PG8_LAS bf16x8*)(lds + PG8_SB(b, h) + boff + n * 2048 + k * 1024); } while (0)
; #define PG8_MMA(ai, bj, At, Bt) do { __builtin_amdgcn_s_setprio(1); _Pragma("unroll") for (int m = 0; m < 4; ++m) _Pragma("unroll") for (int n = 0; n < 2; ++n) _Pragma("unroll") for (int k = 0; k < 2; ++k) \
;         acc[ai][bj][m][n] = __builtin_amdgcn_mfma_f32_16x16x32_bf16(Bt[n][k], At[m][k], acc[ai][bj][m][n], 0, 0, 0); __builtin_amdgcn_s_setprio(0); } while (0)
; #define PG8_WAIT_V(n) asm volatile("s_waitcnt vmcnt(" #n ")" ::: "memory")
; #define PG8_WAIT_L(n) asm volatile("s_waitcnt lgkmcnt(" #n ")" ::: "memory")
; #define PG8_BAR __builtin_amdgcn_s_barrier()
; #define PG8_SCHED __builtin_amdgcn_sched_barrier(0)
;     ...
;         for (int t = 0; t < nt; t += 2) {
;             const bool last = (t == nt - 2);
;             const char* a1 = cA + (size_t)(t + 1) * kstep;
;             const char* a2 = last ? nA : cA + (size_t)(t + 2) * kstep; const char* b2 = last ? nB : cB + (size_t)(t + 2) * kstep;
;             const char* a3 = a2 + kstep; const char* b3 = b2 + kstep;
;             if (last && has_next) S.a_ready(nxt);
;             if constexpr (SP2) {
;             PG8_LDB(B0, 0, 0); PG8_LDB(B1, 0, 1); PG8_SCHED; PG8_LDA(At, 0, 0); PG8_STAGE(PG8_SA(1, 1), a1 + hstep, voffA);
;             PG8_WAIT_V(8); PG8_WAIT_L(0); PG8_BAR; PG8_MMA(0, 0, At, B0); PG8_MMA(0, 1, At, B1); PG8_BAR; PG8_SCHED;
;             PG8_LDA(At, 0, 1); PG8_STAGE(PG8_SB(0, 0), b2, voffB); PG8_STAGE(PG8_SB(0, 1), b2 + hstep, voffB); PG8_STAGE(PG8_SA(0, 0), a2, voffA);
;             PG8_WAIT_V(8); PG8_WAIT_L(0); PG8_BAR; PG8_MMA(1, 0, At, B0); PG8_MMA(1, 1, At, B1); PG8_BAR; PG8_SCHED;
.LBB0_582:
	s_lshl_b32 s30, s56, 7
	s_add_u32 s36, s22, s30
	s_addc_u32 s37, s23, 0
	s_add_i32 s35, s56, 2
	s_lshl_b32 s38, s35, 7
	s_add_u32 s39, s22, s38
	s_addc_u32 s57, s23, 0
	s_and_b64 s[30:31], s[28:29], exec
	s_cselect_b32 s31, s11, s57
	s_cselect_b32 s30, s53, s39
	s_add_u32 s38, s20, s38
	s_addc_u32 s39, s21, 0
	s_and_b64 s[28:29], s[28:29], exec
	s_cselect_b32 s29, s13, s39
	s_cselect_b32 s28, s54, s38
	s_add_i32 s38, 0, 0x10000
	v_add_u32_e32 v138, s38, v142
	s_add_i32 s39, 0, 0x14000
	ds_read_b128 v[146:149], v138
	ds_read_b128 v[150:153], v138 offset:1024
	ds_read_b128 v[154:157], v138 offset:2048
	ds_read_b128 v[158:161], v138 offset:3072
	v_add_u32_e32 v138, s39, v142
	ds_read_b128 v[162:165], v138
	ds_read_b128 v[166:169], v138 offset:1024
	ds_read_b128 v[170:173], v138 offset:2048
	ds_read_b128 v[174:177], v138 offset:3072
	s_add_u32 s36, s36, 0x80080
	s_addc_u32 s37, s37, 0
	v_lshl_add_u64 v[138:139], s[36:37], 0, v[130:131]
	s_add_i32 m0, s44, 0xc000
	ds_read_b128 v[178:181], v144
	ds_read_b128 v[182:185], v144 offset:1024
	ds_read_b128 v[186:189], v144 offset:2048
	ds_read_b128 v[190:193], v144 offset:3072
	ds_read_b128 v[200:203], v144 offset:4096
	ds_read_b128 v[204:207], v144 offset:5120
	ds_read_b128 v[208:211], v144 offset:6144
	ds_read_b128 v[212:215], v144 offset:7168
	global_load_lds_dwordx4 v[138:139], off
	v_lshl_add_u64 v[138:139], s[36:37], 0, v[134:135]
	s_add_i32 m0, s44, 0xe000
	s_nop 0
	global_load_lds_dwordx4 v[138:139], off
	s_waitcnt vmcnt(8)
	s_waitcnt lgkmcnt(0)
	s_barrier
	v_mfma_f32_16x16x32_bf16 v[126:129], v[146:149], v[178:181], v[126:129]
	v_mfma_f32_16x16x32_bf16 v[118:121], v[154:157], v[178:181], v[118:121]
	v_mfma_f32_16x16x32_bf16 v[110:113], v[146:149], v[186:189], v[110:113]
	v_mfma_f32_16x16x32_bf16 v[102:105], v[154:157], v[186:189], v[102:105]
	v_mfma_f32_16x16x32_bf16 v[94:97], v[146:149], v[200:203], v[94:97]
	v_mfma_f32_16x16x32_bf16 v[86:89], v[154:157], v[200:203], v[86:89]
	v_mfma_f32_16x16x32_bf16 v[78:81], v[146:149], v[208:211], v[78:81]
	v_mfma_f32_16x16x32_bf16 v[70:73], v[154:157], v[208:211], v[70:73]
	v_mfma_f32_16x16x32_bf16 v[126:129], v[150:153], v[182:185], v[126:129]
	v_mfma_f32_16x16x32_bf16 v[118:121], v[158:161], v[182:185], v[118:121]
	v_mfma_f32_16x16x32_bf16 v[110:113], v[150:153], v[190:193], v[110:113]
	v_mfma_f32_16x16x32_bf16 v[102:105], v[158:161], v[190:193], v[102:105]
	v_mfma_f32_16x16x32_bf16 v[94:97], v[150:153], v[204:207], v[94:97]
	v_mfma_f32_16x16x32_bf16 v[86:89], v[158:161], v[204:207], v[86:89]
	v_mfma_f32_16x16x32_bf16 v[78:81], v[150:153], v[212:215], v[78:81]
	v_mfma_f32_16x16x32_bf16 v[70:73], v[158:161], v[212:215], v[70:73]
	v_mfma_f32_16x16x32_bf16 v[122:125], v[162:165], v[178:181], v[122:125]
	v_mfma_f32_16x16x32_bf16 v[114:117], v[170:173], v[178:181], v[114:117]
	v_mfma_f32_16x16x32_bf16 v[106:109], v[162:165], v[186:189], v[106:109]
	v_mfma_f32_16x16x32_bf16 v[98:101], v[170:173], v[186:189], v[98:101]
	v_mfma_f32_16x16x32_bf16 v[90:93], v[162:165], v[200:203], v[90:93]
	v_mfma_f32_16x16x32_bf16 v[82:85], v[170:173], v[200:203], v[82:85]
	v_mfma_f32_16x16x32_bf16 v[74:77], v[162:165], v[208:211], v[74:77]
	v_mfma_f32_16x16x32_bf16 v[66:69], v[170:173], v[208:211], v[66:69]
	v_mfma_f32_16x16x32_bf16 v[122:125], v[166:169], v[182:185], v[122:125]
	v_mfma_f32_16x16x32_bf16 v[114:117], v[174:177], v[182:185], v[114:117]
	v_mfma_f32_16x16x32_bf16 v[106:109], v[166:169], v[190:193], v[106:109]
	v_mfma_f32_16x16x32_bf16 v[98:101], v[174:177], v[190:193], v[98:101]
	v_mfma_f32_16x16x32_bf16 v[90:93], v[166:169], v[204:207], v[90:93]
	v_mfma_f32_16x16x32_bf16 v[82:85], v[174:177], v[204:207], v[82:85]
	v_mfma_f32_16x16x32_bf16 v[74:77], v[166:169], v[212:215], v[74:77]
	v_mfma_f32_16x16x32_bf16 v[66:69], v[174:177], v[212:215], v[66:69]
	s_barrier
	s_add_i32 s36, s38, s43
	v_lshl_add_u64 v[138:139], s[28:29], 0, v[132:133]
	s_mov_b32 m0, s36
	ds_read_b128 v[178:181], v144 offset:16384
	ds_read_b128 v[182:185], v144 offset:17408
	ds_read_b128 v[186:189], v144 offset:18432
	ds_read_b128 v[190:193], v144 offset:19456
	ds_read_b128 v[200:203], v144 offset:20480
	ds_read_b128 v[204:207], v144 offset:21504
	ds_read_b128 v[208:211], v144 offset:22528
	ds_read_b128 v[212:215], v144 offset:23552
	global_load_lds_dwordx4 v[138:139], off
	s_add_i32 m0, s36, 0x2000
	s_add_u32 s36, s28, 0x80000
	v_lshl_add_u64 v[220:221], s[28:29], 0, v[136:137]
	s_addc_u32 s37, s29, 0
	s_add_i32 s38, s39, s43
	global_load_lds_dwordx4 v[220:221], off
	v_lshl_add_u64 v[222:223], s[36:37], 0, v[132:133]
	s_mov_b32 m0, s38
	v_lshl_add_u64 v[230:231], s[30:31], 0, v[134:135]
	global_load_lds_dwordx4 v[222:223], off
	v_lshl_add_u64 v[222:223], s[36:37], 0, v[136:137]
	s_add_i32 m0, s38, 0x2000
	s_nop 0
	global_load_lds_dwordx4 v[222:223], off
	v_lshl_add_u64 v[222:223], s[30:31], 0, v[130:131]
	s_mov_b32 m0, s44
	s_nop 0
	global_load_lds_dwordx4 v[222:223], off
	s_mov_b32 m0, s45
	s_nop 0
	global_load_lds_dwordx4 v[230:231], off
	s_waitcnt vmcnt(8)
	s_waitcnt lgkmcnt(0)
	s_barrier
; #define PG8_STAGE(bufoff, gbase, voff) do { _Pragma("unroll") for (int _i = 0; _i < 2; ++_i) \
;         __builtin_amdgcn_global_load_lds((const unsigned*)((const char*)(gbase) + (voff)[_i]), (PG8_LAS unsigned*)(lds + (bufoff) + ldsw + _i * 8192), 16, 0, PG8_AUX_##voff); } while (0)
; #define PG8_LDA(dst, b, h) do { _Pragma("unroll") for (int m = 0; m < 4; ++m) _Pragma("unroll") for (int k = 0; k < 2; ++k) dst[m][k] = *(const PG8_LAS bf16x8*)(lds + PG8_SA(b, h) + aoff + m * 2048 + k * 1024); } while (0)
; #define PG8_LDB(dst, b, h) do { _Pragma("unroll") for (int n = 0; n < 2; ++n) _Pragma("unroll") for (int k = 0; k < 2; ++k) dst[n][k] = *(const PG8_LAS bf16x8*)(lds + PG8_SB(b, h) + boff + n * 2048 + k * 1024); } while (0)
; #define PG8_MMA(ai, bj, At, Bt) do { __builtin_amdgcn_s_setprio(1); _Pragma("unroll") for (int m = 0; m < 4; ++m) _Pragma("unroll") for (int n = 0; n < 2; ++n) _Pragma("unroll") for (int k = 0; k < 2; ++k) \
;         acc[ai][bj][m][n] = __builtin_amdgcn_mfma_f32_16x16x32_bf16(Bt[n][k], At[m][k], acc[ai][bj][m][n], 0, 0, 0); __builtin_amdgcn_s_setprio(0); } while (0)
; #define PG8_WAIT_V(n) asm volatile("s_waitcnt vmcnt(" #n ")" ::: "memory")
; #define PG8_WAIT_L(n) asm volatile("s_waitcnt lgkmcnt(" #n ")" ::: "memory")
; #define PG8_BAR __builtin_amdgcn_s_barrier()
; #define PG8_SCHED __builtin_amdgcn_sched_barrier(0)
;     ...
;             PG8_WAIT_V(8); PG8_WAIT_L(0); PG8_BAR; PG8_MMA(1, 0, At, B0); PG8_MMA(1, 1, At, B1); PG8_BAR; PG8_SCHED;
;             PG8_LDB(B0, 1, 0); PG8_LDB(B1, 1, 1); PG8_SCHED; PG8_LDA(At, 1, 0); PG8_STAGE(PG8_SA(0, 1), a2 + hstep, voffA);
;             PG8_WAIT_V(8); PG8_WAIT_L(0); PG8_BAR; PG8_MMA(0, 0, At, B0); PG8_MMA(0, 1, At, B1); PG8_BAR; PG8_SCHED;
	v_mfma_f32_16x16x32_bf16 v[62:65], v[146:149], v[178:181], v[62:65]
	v_mfma_f32_16x16x32_bf16 v[54:57], v[154:157], v[178:181], v[54:57]
	v_mfma_f32_16x16x32_bf16 v[46:49], v[146:149], v[186:189], v[46:49]
	v_mfma_f32_16x16x32_bf16 v[38:41], v[154:157], v[186:189], v[38:41]
	v_mfma_f32_16x16x32_bf16 v[30:33], v[146:149], v[200:203], v[30:33]
	v_mfma_f32_16x16x32_bf16 v[22:25], v[154:157], v[200:203], v[22:25]
	v_mfma_f32_16x16x32_bf16 v[14:17], v[146:149], v[208:211], v[14:17]
	v_mfma_f32_16x16x32_bf16 v[6:9], v[154:157], v[208:211], v[6:9]
	v_mfma_f32_16x16x32_bf16 v[62:65], v[150:153], v[182:185], v[62:65]
	v_mfma_f32_16x16x32_bf16 v[54:57], v[158:161], v[182:185], v[54:57]
	v_mfma_f32_16x16x32_bf16 v[46:49], v[150:153], v[190:193], v[46:49]
	v_mfma_f32_16x16x32_bf16 v[38:41], v[158:161], v[190:193], v[38:41]
	v_mfma_f32_16x16x32_bf16 v[30:33], v[150:153], v[204:207], v[30:33]
	v_mfma_f32_16x16x32_bf16 v[22:25], v[158:161], v[204:207], v[22:25]
	v_mfma_f32_16x16x32_bf16 v[14:17], v[150:153], v[212:215], v[14:17]
	v_mfma_f32_16x16x32_bf16 v[6:9], v[158:161], v[212:215], v[6:9]
	v_mfma_f32_16x16x32_bf16 v[58:61], v[162:165], v[178:181], v[58:61]
	v_mfma_f32_16x16x32_bf16 v[50:53], v[170:173], v[178:181], v[50:53]
	v_mfma_f32_16x16x32_bf16 v[42:45], v[162:165], v[186:189], v[42:45]
	v_mfma_f32_16x16x32_bf16 v[34:37], v[170:173], v[186:189], v[34:37]
	v_mfma_f32_16x16x32_bf16 v[26:29], v[162:165], v[200:203], v[26:29]
	v_mfma_f32_16x16x32_bf16 v[18:21], v[170:173], v[200:203], v[18:21]
	v_mfma_f32_16x16x32_bf16 v[10:13], v[162:165], v[208:211], v[10:13]
	v_mfma_f32_16x16x32_bf16 v[2:5], v[170:173], v[208:211], v[2:5]
	v_mfma_f32_16x16x32_bf16 v[58:61], v[166:169], v[182:185], v[58:61]
	v_mfma_f32_16x16x32_bf16 v[50:53], v[174:177], v[182:185], v[50:53]
	v_mfma_f32_16x16x32_bf16 v[42:45], v[166:169], v[190:193], v[42:45]
	v_mfma_f32_16x16x32_bf16 v[34:37], v[174:177], v[190:193], v[34:37]
	v_mfma_f32_16x16x32_bf16 v[26:29], v[166:169], v[204:207], v[26:29]
	v_mfma_f32_16x16x32_bf16 v[18:21], v[174:177], v[204:207], v[18:21]
	v_mfma_f32_16x16x32_bf16 v[10:13], v[166:169], v[212:215], v[10:13]
	v_mfma_f32_16x16x32_bf16 v[2:5], v[174:177], v[212:215], v[2:5]
	s_barrier
	s_add_i32 s36, 0, 0x18000
	v_add_u32_e32 v145, s36, v142
	s_add_i32 s37, 0, 0x1c000
	ds_read_b128 v[146:149], v145
	ds_read_b128 v[150:153], v145 offset:1024
	ds_read_b128 v[154:157], v145 offset:2048
	ds_read_b128 v[158:161], v145 offset:3072
	v_add_u32_e32 v145, s37, v142
	ds_read_b128 v[162:165], v145
	ds_read_b128 v[166:169], v145 offset:1024
	ds_read_b128 v[170:173], v145 offset:2048
	ds_read_b128 v[174:177], v145 offset:3072
	s_add_u32 s30, s30, 0x80000
	s_addc_u32 s31, s31, 0
	s_mov_b32 m0, s46
	v_lshl_add_u64 v[232:233], s[30:31], 0, v[130:131]
	ds_read_b128 v[178:181], v144 offset:32768
	ds_read_b128 v[182:185], v144 offset:33792
	ds_read_b128 v[186:189], v144 offset:34816
	ds_read_b128 v[190:193], v144 offset:35840
	ds_read_b128 v[200:203], v144 offset:36864
	ds_read_b128 v[204:207], v144 offset:37888
	ds_read_b128 v[208:211], v144 offset:38912
	ds_read_b128 v[212:215], v144 offset:39936
	global_load_lds_dwordx4 v[232:233], off
	v_lshl_add_u64 v[232:233], s[30:31], 0, v[134:135]
	s_mov_b32 m0, s47
	s_nop 0
	global_load_lds_dwordx4 v[232:233], off
	s_waitcnt vmcnt(8)
	s_waitcnt lgkmcnt(0)
	s_barrier
	v_mfma_f32_16x16x32_bf16 v[126:129], v[146:149], v[178:181], v[126:129]
	v_mfma_f32_16x16x32_bf16 v[118:121], v[154:157], v[178:181], v[118:121]
	v_mfma_f32_16x16x32_bf16 v[110:113], v[146:149], v[186:189], v[110:113]
	v_mfma_f32_16x16x32_bf16 v[102:105], v[154:157], v[186:189], v[102:105]
	v_mfma_f32_16x16x32_bf16 v[94:97], v[146:149], v[200:203], v[94:97]
	v_mfma_f32_16x16x32_bf16 v[86:89], v[154:157], v[200:203], v[86:89]
	v_mfma_f32_16x16x32_bf16 v[78:81], v[146:149], v[208:211], v[78:81]
	v_mfma_f32_16x16x32_bf16 v[70:73], v[154:157], v[208:211], v[70:73]
	v_mfma_f32_16x16x32_bf16 v[126:129], v[150:153], v[182:185], v[126:129]
	v_mfma_f32_16x16x32_bf16 v[118:121], v[158:161], v[182:185], v[118:121]
	v_mfma_f32_16x16x32_bf16 v[110:113], v[150:153], v[190:193], v[110:113]
	v_mfma_f32_16x16x32_bf16 v[102:105], v[158:161], v[190:193], v[102:105]
	v_mfma_f32_16x16x32_bf16 v[94:97], v[150:153], v[204:207], v[94:97]
	v_mfma_f32_16x16x32_bf16 v[86:89], v[158:161], v[204:207], v[86:89]
	v_mfma_f32_16x16x32_bf16 v[78:81], v[150:153], v[212:215], v[78:81]
	v_mfma_f32_16x16x32_bf16 v[70:73], v[158:161], v[212:215], v[70:73]
	v_mfma_f32_16x16x32_bf16 v[122:125], v[162:165], v[178:181], v[122:125]
	v_mfma_f32_16x16x32_bf16 v[114:117], v[170:173], v[178:181], v[114:117]
	v_mfma_f32_16x16x32_bf16 v[106:109], v[162:165], v[186:189], v[106:109]
	v_mfma_f32_16x16x32_bf16 v[98:101], v[170:173], v[186:189], v[98:101]
	v_mfma_f32_16x16x32_bf16 v[90:93], v[162:165], v[200:203], v[90:93]
	v_mfma_f32_16x16x32_bf16 v[82:85], v[170:173], v[200:203], v[82:85]
	v_mfma_f32_16x16x32_bf16 v[74:77], v[162:165], v[208:211], v[74:77]
	v_mfma_f32_16x16x32_bf16 v[66:69], v[170:173], v[208:211], v[66:69]
	v_mfma_f32_16x16x32_bf16 v[122:125], v[166:169], v[182:185], v[122:125]
	v_mfma_f32_16x16x32_bf16 v[114:117], v[174:177], v[182:185], v[114:117]
	v_mfma_f32_16x16x32_bf16 v[106:109], v[166:169], v[190:193], v[106:109]
	v_mfma_f32_16x16x32_bf16 v[98:101], v[174:177], v[190:193], v[98:101]
	v_mfma_f32_16x16x32_bf16 v[90:93], v[166:169], v[204:207], v[90:93]
	v_mfma_f32_16x16x32_bf16 v[82:85], v[174:177], v[204:207], v[82:85]
	v_mfma_f32_16x16x32_bf16 v[74:77], v[166:169], v[212:215], v[74:77]
	v_mfma_f32_16x16x32_bf16 v[66:69], v[174:177], v[212:215], v[66:69]
	s_barrier
; #define PG8_STAGE(bufoff, gbase, voff) do { _Pragma("unroll") for (int _i = 0; _i < 2; ++_i) \
;         __builtin_amdgcn_global_load_lds((const unsigned*)((const char*)(gbase) + (voff)[_i]), (PG8_LAS unsigned*)(lds + (bufoff) + ldsw + _i * 8192), 16, 0, PG8_AUX_##voff); } while (0)
; #define PG8_LDA(dst, b, h) do { _Pragma("unroll") for (int m = 0; m < 4; ++m) _Pragma("unroll") for (int k = 0; k < 2; ++k) dst[m][k] = *(const PG8_LAS bf16x8*)(lds + PG8_SA(b, h) + aoff + m * 2048 + k * 1024); } while (0)
; #define PG8_LDB(dst, b, h) do { _Pragma("unroll") for (int n = 0; n < 2; ++n) _Pragma("unroll") for (int k = 0; k < 2; ++k) dst[n][k] = *(const PG8_LAS bf16x8*)(lds + PG8_SB(b, h) + boff + n * 2048 + k * 1024); } while (0)
; #define PG8_WAIT_V(n) asm volatile("s_waitcnt vmcnt(" #n ")" ::: "memory")
; #define PG8_WAIT_L(n) asm volatile("s_waitcnt lgkmcnt(" #n ")" ::: "memory")
;     ...
;         for (int t = 0; t < nt; t += 2) {
;             const bool last = (t == nt - 2);
;             const char* a1 = cA + (size_t)(t + 1) * kstep;
;             const char* a2 = last ? nA : cA + (size_t)(t + 2) * kstep; const char* b2 = last ? nB : cB + (size_t)(t + 2) * kstep;
;             const char* a3 = a2 + kstep; const char* b3 = b2 + kstep;
;             if (last && has_next) S.a_ready(nxt);
;             if constexpr (SP2) {
;             PG8_LDB(B0, 0, 0); PG8_LDB(B1, 0, 1); PG8_SCHED; PG8_LDA(At, 0, 0); PG8_STAGE(PG8_SA(1, 1), a1 + hstep, voffA);
;             PG8_WAIT_V(8); PG8_WAIT_L(0); PG8_BAR; PG8_MMA(0, 0, At, B0); PG8_MMA(0, 1, At, B1); PG8_BAR; PG8_SCHED;
;             PG8_LDA(At, 0, 1); PG8_STAGE(PG8_SB(0, 0), b2, voffB); PG8_STAGE(PG8_SB(0, 1), b2 + hstep, voffB); PG8_STAGE(PG8_SA(0, 0), a2, voffA);
;             PG8_WAIT_V(8); PG8_WAIT_L(0); PG8_BAR; PG8_MMA(1, 0, At, B0); PG8_MMA(1, 1, At, B1); PG8_BAR; PG8_SCHED;
;             PG8_LDB(B0, 1, 0); PG8_LDB(B1, 1, 1); PG8_SCHED; PG8_LDA(At, 1, 0); PG8_STAGE(PG8_SA(0, 1), a2 + hstep, voffA);
;             PG8_WAIT_V(8); PG8_WAIT_L(0); PG8_BAR; PG8_MMA(0, 0, At, B0); PG8_MMA(0, 1, At, B1); PG8_BAR; PG8_SCHED;
;             PG8_LDA(At, 1, 1); PG8_STAGE(PG8_SB(1, 0), b3, voffB); PG8_STAGE(PG8_SB(1, 1), b3 + hstep, voffB); PG8_STAGE(PG8_SA(1, 0), a3, voffA);
;             PG8_WAIT_V(8); PG8_WAIT_L(0); PG8_BAR; PG8_MMA(1, 0, At, B0); PG8_MMA(1, 1, At, B1); PG8_BAR; PG8_SCHED;
	s_add_i32 s30, s36, s43
	v_lshl_add_u64 v[138:139], v[138:139], 0, s[2:3]
	s_mov_b32 m0, s30
	ds_read_b128 v[178:181], v144 offset:49152
	ds_read_b128 v[182:185], v144 offset:50176
	ds_read_b128 v[186:189], v144 offset:51200
	ds_read_b128 v[190:193], v144 offset:52224
	ds_read_b128 v[200:203], v144 offset:53248
	ds_read_b128 v[204:207], v144 offset:54272
	ds_read_b128 v[208:211], v144 offset:55296
	ds_read_b128 v[212:215], v144 offset:56320
	global_load_lds_dwordx4 v[138:139], off
	s_add_i32 m0, s30, 0x2000
	s_add_u32 s28, s28, 0x80080
	v_lshl_add_u64 v[138:139], v[220:221], 0, s[2:3]
	s_addc_u32 s29, s29, 0
	s_add_i32 s30, s37, s43
	global_load_lds_dwordx4 v[138:139], off
	v_lshl_add_u64 v[138:139], s[28:29], 0, v[132:133]
	s_mov_b32 m0, s30
	s_nop 0
	global_load_lds_dwordx4 v[138:139], off
	v_lshl_add_u64 v[138:139], s[28:29], 0, v[136:137]
	s_add_i32 m0, s30, 0x2000
	s_nop 0
	global_load_lds_dwordx4 v[138:139], off
	v_lshl_add_u64 v[138:139], v[222:223], 0, s[2:3]
	s_mov_b32 m0, s48
	s_nop 0
	global_load_lds_dwordx4 v[138:139], off
	v_lshl_add_u64 v[138:139], v[230:231], 0, s[2:3]
	s_mov_b32 m0, s49
	s_nop 0
	global_load_lds_dwordx4 v[138:139], off
	s_waitcnt vmcnt(8)
	s_waitcnt lgkmcnt(0)
	s_barrier
	v_mfma_f32_16x16x32_bf16 v[62:65], v[146:149], v[178:181], v[62:65]
	v_mfma_f32_16x16x32_bf16 v[54:57], v[154:157], v[178:181], v[54:57]
	v_mfma_f32_16x16x32_bf16 v[46:49], v[146:149], v[186:189], v[46:49]
	v_mfma_f32_16x16x32_bf16 v[38:41], v[154:157], v[186:189], v[38:41]
	v_mfma_f32_16x16x32_bf16 v[30:33], v[146:149], v[200:203], v[30:33]
	v_mfma_f32_16x16x32_bf16 v[22:25], v[154:157], v[200:203], v[22:25]
	v_mfma_f32_16x16x32_bf16 v[14:17], v[146:149], v[208:211], v[14:17]
	v_mfma_f32_16x16x32_bf16 v[6:9], v[154:157], v[208:211], v[6:9]
	v_mfma_f32_16x16x32_bf16 v[62:65], v[150:153], v[182:185], v[62:65]
	v_mfma_f32_16x16x32_bf16 v[54:57], v[158:161], v[182:185], v[54:57]
	v_mfma_f32_16x16x32_bf16 v[46:49], v[150:153], v[190:193], v[46:49]
	v_mfma_f32_16x16x32_bf16 v[38:41], v[158:161], v[190:193], v[38:41]
	v_mfma_f32_16x16x32_bf16 v[30:33], v[150:153], v[204:207], v[30:33]
	v_mfma_f32_16x16x32_bf16 v[22:25], v[158:161], v[204:207], v[22:25]
	v_mfma_f32_16x16x32_bf16 v[14:17], v[150:153], v[212:215], v[14:17]
	v_mfma_f32_16x16x32_bf16 v[6:9], v[158:161], v[212:215], v[6:9]
	v_mfma_f32_16x16x32_bf16 v[58:61], v[162:165], v[178:181], v[58:61]
	v_mfma_f32_16x16x32_bf16 v[50:53], v[170:173], v[178:181], v[50:53]
	v_mfma_f32_16x16x32_bf16 v[42:45], v[162:165], v[186:189], v[42:45]
	v_mfma_f32_16x16x32_bf16 v[34:37], v[170:173], v[186:189], v[34:37]
	v_mfma_f32_16x16x32_bf16 v[26:29], v[162:165], v[200:203], v[26:29]
	v_mfma_f32_16x16x32_bf16 v[18:21], v[170:173], v[200:203], v[18:21]
	v_mfma_f32_16x16x32_bf16 v[10:13], v[162:165], v[208:211], v[10:13]
	v_mfma_f32_16x16x32_bf16 v[2:5], v[170:173], v[208:211], v[2:5]
	v_mfma_f32_16x16x32_bf16 v[58:61], v[166:169], v[182:185], v[58:61]
	v_mfma_f32_16x16x32_bf16 v[50:53], v[174:177], v[182:185], v[50:53]
	v_mfma_f32_16x16x32_bf16 v[42:45], v[166:169], v[190:193], v[42:45]
	v_mfma_f32_16x16x32_bf16 v[34:37], v[174:177], v[190:193], v[34:37]
	v_mfma_f32_16x16x32_bf16 v[26:29], v[166:169], v[204:207], v[26:29]
	v_mfma_f32_16x16x32_bf16 v[18:21], v[174:177], v[204:207], v[18:21]
	v_mfma_f32_16x16x32_bf16 v[10:13], v[166:169], v[212:215], v[10:13]
	v_mfma_f32_16x16x32_bf16 v[2:5], v[174:177], v[212:215], v[2:5]
	s_barrier
	s_cmp_gt_u32 s56, 29
	s_cbranch_scc1 .LBB0_584
	s_mov_b32 s56, s35
	s_branch .LBB0_565

; #define PG8_STAGE(bufoff, gbase, voff) do { _Pragma("unroll") for (int _i = 0; _i < 2; ++_i) \
;         __builtin_amdgcn_global_load_lds((const unsigned*)((const char*)(gbase) + (voff)[_i]), (PG8_LAS unsigned*)(lds + (bufoff) + ldsw + _i * 8192), 16, 0, PG8_AUX_##voff); } while (0)
; #define PG8_LDA(dst, b, h) do { _Pragma("unroll") for (int m = 0; m < 4; ++m) _Pragma("unroll") for (int k = 0; k < 2; ++k) dst[m][k] = *(const PG8_LAS bf16x8*)(lds + PG8_SA(b, h) + aoff + m * 2048 + k * 1024); } while (0)
; #define PG8_LDB(dst, b, h) do { _Pragma("unroll") for (int n = 0; n < 2; ++n) _Pragma("unroll") for (int k = 0; k < 2; ++k) dst[n][k] = *(const PG8_LAS bf16x8*)(lds + PG8_SB(b, h) + boff + n * 2048 + k * 1024); } while (0)
; #define PG8_MMA(ai, bj, At, Bt) do { __builtin_amdgcn_s_setprio(1); _Pragma("unroll") for (int m = 0; m < 4; ++m) _Pragma("unroll") for (int n = 0; n < 2; ++n) _Pragma("unroll") for (int k = 0; k < 2; ++k) \
;         acc[ai][bj][m][n] = __builtin_amdgcn_mfma_f32_16x16x32_bf16(Bt[n][k], At[m][k], acc[ai][bj][m][n], 0, 0, 0); __builtin_amdgcn_s_setprio(0); } while (0)
; #define PG8_WAIT_V(n) asm volatile("s_waitcnt vmcnt(" #n ")" ::: "memory")
; #define PG8_WAIT_L(n) asm volatile("s_waitcnt lgkmcnt(" #n ")" ::: "memory")
; #define PG8_BAR __builtin_amdgcn_s_barrier()
; #define PG8_SCHED __builtin_amdgcn_sched_barrier(0)
;     ...
;         for (int t = 0; t < nt; t += 2) {
;             const bool last = (t == nt - 2);
;             const char* a1 = cA + (size_t)(t + 1) * kstep;
;             const char* a2 = last ? nA : cA + (size_t)(t + 2) * kstep; const char* b2 = last ? nB : cB + (size_t)(t + 2) * kstep;
;             const char* a3 = a2 + kstep; const char* b3 = b2 + kstep;
;             if (last && has_next) S.a_ready(nxt);
;             if constexpr (SP2) {
;             PG8_LDB(B0, 0, 0); PG8_LDB(B1, 0, 1); PG8_SCHED; PG8_LDA(At, 0, 0); PG8_STAGE(PG8_SA(1, 1), a1 + hstep, voffA);
;             PG8_WAIT_V(8); PG8_WAIT_L(0); PG8_BAR; PG8_MMA(0, 0, At, B0); PG8_MMA(0, 1, At, B1); PG8_BAR; PG8_SCHED;
;             PG8_LDA(At, 0, 1); PG8_STAGE(PG8_SB(0, 0), b2, voffB); PG8_STAGE(PG8_SB(0, 1), b2 + hstep, voffB); PG8_STAGE(PG8_SA(0, 0), a2, voffA);
;             PG8_WAIT_V(8); PG8_WAIT_L(0); PG8_BAR; PG8_MMA(1, 0, At, B0); PG8_MMA(1, 1, At, B1); PG8_BAR; PG8_SCHED;
.LBB0_809:
	s_add_u32 s26, s22, s24
	s_addc_u32 s27, s23, s25
	s_add_u32 s53, s20, s24
	s_addc_u32 s54, s21, s25
	s_add_i32 s55, 0, 0x10000
	s_cmp_eq_u32 s11, s17
	s_cselect_b32 s29, s5, s27
	s_cselect_b32 s28, s4, s26
	s_cselect_b32 s27, s19, s54
	s_cselect_b32 s26, s18, s53
	s_add_i32 s53, 0, 0x14000
	v_add_u32_e32 v162, s55, v146
	v_add_u32_e32 v178, s53, v146
	ds_read_b128 v[150:153], v162
	ds_read_b128 v[154:157], v162 offset:1024
	ds_read_b128 v[158:161], v162 offset:2048
	ds_read_b128 v[162:165], v162 offset:3072
	ds_read_b128 v[166:169], v178
	ds_read_b128 v[170:173], v178 offset:1024
	ds_read_b128 v[174:177], v178 offset:2048
	ds_read_b128 v[178:181], v178 offset:3072
	v_lshl_add_u64 v[214:215], s[22:23], 0, v[142:143]
	s_add_i32 m0, s40, 0xc000
	ds_read_b128 v[182:185], v149
	ds_read_b128 v[186:189], v149 offset:1024
	ds_read_b128 v[190:193], v149 offset:2048
	ds_read_b128 v[200:203], v149 offset:3072
	ds_read_b128 v[204:207], v149 offset:4096
	ds_read_b128 v[208:211], v149 offset:5120
	ds_read_b128 v[232:235], v149 offset:6144
	ds_read_b128 v[236:239], v149 offset:7168
	global_load_lds_dwordx4 v[214:215], off
	v_lshl_add_u64 v[214:215], s[22:23], 0, v[140:141]
	s_add_i32 m0, s40, 0xe000
	s_nop 0
	global_load_lds_dwordx4 v[214:215], off
	s_waitcnt vmcnt(8)
	s_waitcnt lgkmcnt(0)
	s_barrier
	v_mfma_f32_16x16x32_bf16 v[98:101], v[150:153], v[182:185], v[98:101]
	v_mfma_f32_16x16x32_bf16 v[102:105], v[158:161], v[182:185], v[102:105]
	v_mfma_f32_16x16x32_bf16 v[126:129], v[150:153], v[190:193], v[126:129]
	v_mfma_f32_16x16x32_bf16 v[122:125], v[158:161], v[190:193], v[122:125]
	v_mfma_f32_16x16x32_bf16 v[94:97], v[150:153], v[204:207], v[94:97]
	v_mfma_f32_16x16x32_bf16 v[90:93], v[158:161], v[204:207], v[90:93]
	v_mfma_f32_16x16x32_bf16 v[78:81], v[150:153], v[232:235], v[78:81]
	v_mfma_f32_16x16x32_bf16 v[74:77], v[158:161], v[232:235], v[74:77]
	v_mfma_f32_16x16x32_bf16 v[98:101], v[154:157], v[186:189], v[98:101]
	v_mfma_f32_16x16x32_bf16 v[102:105], v[162:165], v[186:189], v[102:105]
	v_mfma_f32_16x16x32_bf16 v[126:129], v[154:157], v[200:203], v[126:129]
	v_mfma_f32_16x16x32_bf16 v[122:125], v[162:165], v[200:203], v[122:125]
	v_mfma_f32_16x16x32_bf16 v[94:97], v[154:157], v[208:211], v[94:97]
	v_mfma_f32_16x16x32_bf16 v[90:93], v[162:165], v[208:211], v[90:93]
	v_mfma_f32_16x16x32_bf16 v[78:81], v[154:157], v[236:239], v[78:81]
	v_mfma_f32_16x16x32_bf16 v[74:77], v[162:165], v[236:239], v[74:77]
	v_mfma_f32_16x16x32_bf16 v[106:109], v[166:169], v[182:185], v[106:109]
	v_mfma_f32_16x16x32_bf16 v[110:113], v[174:177], v[182:185], v[110:113]
	v_mfma_f32_16x16x32_bf16 v[114:117], v[166:169], v[190:193], v[114:117]
	v_mfma_f32_16x16x32_bf16 v[118:121], v[174:177], v[190:193], v[118:121]
	v_mfma_f32_16x16x32_bf16 v[86:89], v[166:169], v[204:207], v[86:89]
	v_mfma_f32_16x16x32_bf16 v[82:85], v[174:177], v[204:207], v[82:85]
	v_mfma_f32_16x16x32_bf16 v[70:73], v[166:169], v[232:235], v[70:73]
	v_mfma_f32_16x16x32_bf16 v[66:69], v[174:177], v[232:235], v[66:69]
	v_mfma_f32_16x16x32_bf16 v[106:109], v[170:173], v[186:189], v[106:109]
	v_mfma_f32_16x16x32_bf16 v[110:113], v[178:181], v[186:189], v[110:113]
	v_mfma_f32_16x16x32_bf16 v[114:117], v[170:173], v[200:203], v[114:117]
	v_mfma_f32_16x16x32_bf16 v[118:121], v[178:181], v[200:203], v[118:121]
	v_mfma_f32_16x16x32_bf16 v[86:89], v[170:173], v[208:211], v[86:89]
	v_mfma_f32_16x16x32_bf16 v[82:85], v[178:181], v[208:211], v[82:85]
	v_mfma_f32_16x16x32_bf16 v[70:73], v[170:173], v[236:239], v[70:73]
	v_mfma_f32_16x16x32_bf16 v[66:69], v[178:181], v[236:239], v[66:69]
	s_barrier
	s_add_i32 s54, s55, s39
	v_lshl_add_u64 v[214:215], s[26:27], 0, v[194:195]
	s_mov_b32 m0, s54
	ds_read_b128 v[182:185], v149 offset:16384
	ds_read_b128 v[186:189], v149 offset:17408
	ds_read_b128 v[190:193], v149 offset:18432
	ds_read_b128 v[200:203], v149 offset:19456
	ds_read_b128 v[204:207], v149 offset:20480
	ds_read_b128 v[208:211], v149 offset:21504
	ds_read_b128 v[232:235], v149 offset:22528
	ds_read_b128 v[236:239], v149 offset:23552
	global_load_lds_dwordx4 v[214:215], off
	s_add_i32 m0, s54, 0x2000
	s_add_u32 s54, s26, 0x160000
	v_lshl_add_u64 v[220:221], s[26:27], 0, v[134:135]
	s_addc_u32 s55, s27, 0
	s_add_i32 s53, s53, s39
	global_load_lds_dwordx4 v[220:221], off
	v_lshl_add_u64 v[222:223], s[54:55], 0, v[194:195]
	s_mov_b32 m0, s53
	v_lshl_add_u64 v[240:241], s[28:29], 0, v[132:133]
	global_load_lds_dwordx4 v[222:223], off
	v_lshl_add_u64 v[222:223], s[54:55], 0, v[134:135]
	s_add_i32 m0, s53, 0x2000
	s_nop 0
	global_load_lds_dwordx4 v[222:223], off
	v_lshl_add_u64 v[222:223], s[28:29], 0, v[130:131]
	s_mov_b32 m0, s40
	s_nop 0
	global_load_lds_dwordx4 v[222:223], off
	s_mov_b32 m0, s42
	s_nop 0
	global_load_lds_dwordx4 v[240:241], off
	s_waitcnt vmcnt(8)
	s_waitcnt lgkmcnt(0)
	s_barrier
; #define PG8_STAGE(bufoff, gbase, voff) do { _Pragma("unroll") for (int _i = 0; _i < 2; ++_i) \
;         __builtin_amdgcn_global_load_lds((const unsigned*)((const char*)(gbase) + (voff)[_i]), (PG8_LAS unsigned*)(lds + (bufoff) + ldsw + _i * 8192), 16, 0, PG8_AUX_##voff); } while (0)
; #define PG8_LDA(dst, b, h) do { _Pragma("unroll") for (int m = 0; m < 4; ++m) _Pragma("unroll") for (int k = 0; k < 2; ++k) dst[m][k] = *(const PG8_LAS bf16x8*)(lds + PG8_SA(b, h) + aoff + m * 2048 + k * 1024); } while (0)
; #define PG8_LDB(dst, b, h) do { _Pragma("unroll") for (int n = 0; n < 2; ++n) _Pragma("unroll") for (int k = 0; k < 2; ++k) dst[n][k] = *(const PG8_LAS bf16x8*)(lds + PG8_SB(b, h) + boff + n * 2048 + k * 1024); } while (0)
; #define PG8_MMA(ai, bj, At, Bt) do { __builtin_amdgcn_s_setprio(1); _Pragma("unroll") for (int m = 0; m < 4; ++m) _Pragma("unroll") for (int n = 0; n < 2; ++n) _Pragma("unroll") for (int k = 0; k < 2; ++k) \
;         acc[ai][bj][m][n] = __builtin_amdgcn_mfma_f32_16x16x32_bf16(Bt[n][k], At[m][k], acc[ai][bj][m][n], 0, 0, 0); __builtin_amdgcn_s_setprio(0); } while (0)
; #define PG8_WAIT_V(n) asm volatile("s_waitcnt vmcnt(" #n ")" ::: "memory")
; #define PG8_WAIT_L(n) asm volatile("s_waitcnt lgkmcnt(" #n ")" ::: "memory")
; #define PG8_BAR __builtin_amdgcn_s_barrier()
; #define PG8_SCHED __builtin_amdgcn_sched_barrier(0)
;     ...
;             PG8_WAIT_V(8); PG8_WAIT_L(0); PG8_BAR; PG8_MMA(1, 0, At, B0); PG8_MMA(1, 1, At, B1); PG8_BAR; PG8_SCHED;
;             PG8_LDB(B0, 1, 0); PG8_LDB(B1, 1, 1); PG8_SCHED; PG8_LDA(At, 1, 0); PG8_STAGE(PG8_SA(0, 1), a2 + hstep, voffA);
;             PG8_WAIT_V(8); PG8_WAIT_L(0); PG8_BAR; PG8_MMA(0, 0, At, B0); PG8_MMA(0, 1, At, B1); PG8_BAR; PG8_SCHED;
	v_mfma_f32_16x16x32_bf16 v[62:65], v[150:153], v[182:185], v[62:65]
	v_mfma_f32_16x16x32_bf16 v[58:61], v[158:161], v[182:185], v[58:61]
	v_mfma_f32_16x16x32_bf16 v[46:49], v[150:153], v[190:193], v[46:49]
	v_mfma_f32_16x16x32_bf16 v[42:45], v[158:161], v[190:193], v[42:45]
	v_mfma_f32_16x16x32_bf16 v[30:33], v[150:153], v[204:207], v[30:33]
	v_mfma_f32_16x16x32_bf16 v[26:29], v[158:161], v[204:207], v[26:29]
	v_mfma_f32_16x16x32_bf16 v[14:17], v[150:153], v[232:235], v[14:17]
	v_mfma_f32_16x16x32_bf16 v[10:13], v[158:161], v[232:235], v[10:13]
	v_mfma_f32_16x16x32_bf16 v[62:65], v[154:157], v[186:189], v[62:65]
	v_mfma_f32_16x16x32_bf16 v[58:61], v[162:165], v[186:189], v[58:61]
	v_mfma_f32_16x16x32_bf16 v[46:49], v[154:157], v[200:203], v[46:49]
	v_mfma_f32_16x16x32_bf16 v[42:45], v[162:165], v[200:203], v[42:45]
	v_mfma_f32_16x16x32_bf16 v[30:33], v[154:157], v[208:211], v[30:33]
	v_mfma_f32_16x16x32_bf16 v[26:29], v[162:165], v[208:211], v[26:29]
	v_mfma_f32_16x16x32_bf16 v[14:17], v[154:157], v[236:239], v[14:17]
	v_mfma_f32_16x16x32_bf16 v[10:13], v[162:165], v[236:239], v[10:13]
	v_mfma_f32_16x16x32_bf16 v[54:57], v[166:169], v[182:185], v[54:57]
	v_mfma_f32_16x16x32_bf16 v[50:53], v[174:177], v[182:185], v[50:53]
	v_mfma_f32_16x16x32_bf16 v[38:41], v[166:169], v[190:193], v[38:41]
	v_mfma_f32_16x16x32_bf16 v[34:37], v[174:177], v[190:193], v[34:37]
	v_mfma_f32_16x16x32_bf16 v[22:25], v[166:169], v[204:207], v[22:25]
	v_mfma_f32_16x16x32_bf16 v[18:21], v[174:177], v[204:207], v[18:21]
	v_mfma_f32_16x16x32_bf16 v[6:9], v[166:169], v[232:235], v[6:9]
	v_mfma_f32_16x16x32_bf16 v[2:5], v[174:177], v[232:235], v[2:5]
	v_mfma_f32_16x16x32_bf16 v[54:57], v[170:173], v[186:189], v[54:57]
	v_mfma_f32_16x16x32_bf16 v[50:53], v[178:181], v[186:189], v[50:53]
	v_mfma_f32_16x16x32_bf16 v[38:41], v[170:173], v[200:203], v[38:41]
	v_mfma_f32_16x16x32_bf16 v[34:37], v[178:181], v[200:203], v[34:37]
	v_mfma_f32_16x16x32_bf16 v[22:25], v[170:173], v[208:211], v[22:25]
	v_mfma_f32_16x16x32_bf16 v[18:21], v[178:181], v[208:211], v[18:21]
	v_mfma_f32_16x16x32_bf16 v[6:9], v[170:173], v[236:239], v[6:9]
	v_mfma_f32_16x16x32_bf16 v[2:5], v[178:181], v[236:239], v[2:5]
	s_barrier
	s_add_i32 s53, 0, 0x18000
	s_add_i32 s54, 0, 0x1c000
	v_add_u32_e32 v162, s53, v146
	v_add_u32_e32 v178, s54, v146
	ds_read_b128 v[150:153], v162
	ds_read_b128 v[154:157], v162 offset:1024
	ds_read_b128 v[158:161], v162 offset:2048
	ds_read_b128 v[162:165], v162 offset:3072
	ds_read_b128 v[166:169], v178
	ds_read_b128 v[170:173], v178 offset:1024
	ds_read_b128 v[174:177], v178 offset:2048
	ds_read_b128 v[178:181], v178 offset:3072
	s_add_u32 s28, s28, 0x160000
	s_addc_u32 s29, s29, 0
	s_mov_b32 m0, s43
	v_lshl_add_u64 v[242:243], s[28:29], 0, v[130:131]
	ds_read_b128 v[182:185], v149 offset:32768
	ds_read_b128 v[186:189], v149 offset:33792
	ds_read_b128 v[190:193], v149 offset:34816
	ds_read_b128 v[200:203], v149 offset:35840
	ds_read_b128 v[204:207], v149 offset:36864
	ds_read_b128 v[208:211], v149 offset:37888
	ds_read_b128 v[232:235], v149 offset:38912
	ds_read_b128 v[236:239], v149 offset:39936
	global_load_lds_dwordx4 v[242:243], off
	v_lshl_add_u64 v[242:243], s[28:29], 0, v[132:133]
	s_mov_b32 m0, s44
	s_nop 0
	global_load_lds_dwordx4 v[242:243], off
	s_waitcnt vmcnt(8)
	s_waitcnt lgkmcnt(0)
	s_barrier
	v_mfma_f32_16x16x32_bf16 v[98:101], v[150:153], v[182:185], v[98:101]
	v_mfma_f32_16x16x32_bf16 v[102:105], v[158:161], v[182:185], v[102:105]
	v_mfma_f32_16x16x32_bf16 v[126:129], v[150:153], v[190:193], v[126:129]
	v_mfma_f32_16x16x32_bf16 v[122:125], v[158:161], v[190:193], v[122:125]
	v_mfma_f32_16x16x32_bf16 v[94:97], v[150:153], v[204:207], v[94:97]
	v_mfma_f32_16x16x32_bf16 v[90:93], v[158:161], v[204:207], v[90:93]
	v_mfma_f32_16x16x32_bf16 v[78:81], v[150:153], v[232:235], v[78:81]
	v_mfma_f32_16x16x32_bf16 v[74:77], v[158:161], v[232:235], v[74:77]
	v_mfma_f32_16x16x32_bf16 v[98:101], v[154:157], v[186:189], v[98:101]
	v_mfma_f32_16x16x32_bf16 v[102:105], v[162:165], v[186:189], v[102:105]
	v_mfma_f32_16x16x32_bf16 v[126:129], v[154:157], v[200:203], v[126:129]
	v_mfma_f32_16x16x32_bf16 v[122:125], v[162:165], v[200:203], v[122:125]
	v_mfma_f32_16x16x32_bf16 v[94:97], v[154:157], v[208:211], v[94:97]
	v_mfma_f32_16x16x32_bf16 v[90:93], v[162:165], v[208:211], v[90:93]
	v_mfma_f32_16x16x32_bf16 v[78:81], v[154:157], v[236:239], v[78:81]
	v_mfma_f32_16x16x32_bf16 v[74:77], v[162:165], v[236:239], v[74:77]
	v_mfma_f32_16x16x32_bf16 v[106:109], v[166:169], v[182:185], v[106:109]
	v_mfma_f32_16x16x32_bf16 v[110:113], v[174:177], v[182:185], v[110:113]
	v_mfma_f32_16x16x32_bf16 v[114:117], v[166:169], v[190:193], v[114:117]
	v_mfma_f32_16x16x32_bf16 v[118:121], v[174:177], v[190:193], v[118:121]
	v_mfma_f32_16x16x32_bf16 v[86:89], v[166:169], v[204:207], v[86:89]
	v_mfma_f32_16x16x32_bf16 v[82:85], v[174:177], v[204:207], v[82:85]
	v_mfma_f32_16x16x32_bf16 v[70:73], v[166:169], v[232:235], v[70:73]
	v_mfma_f32_16x16x32_bf16 v[66:69], v[174:177], v[232:235], v[66:69]
	v_mfma_f32_16x16x32_bf16 v[106:109], v[170:173], v[186:189], v[106:109]
	v_mfma_f32_16x16x32_bf16 v[110:113], v[178:181], v[186:189], v[110:113]
	v_mfma_f32_16x16x32_bf16 v[114:117], v[170:173], v[200:203], v[114:117]
	v_mfma_f32_16x16x32_bf16 v[118:121], v[178:181], v[200:203], v[118:121]
	v_mfma_f32_16x16x32_bf16 v[86:89], v[170:173], v[208:211], v[86:89]
	v_mfma_f32_16x16x32_bf16 v[82:85], v[178:181], v[208:211], v[82:85]
	v_mfma_f32_16x16x32_bf16 v[70:73], v[170:173], v[236:239], v[70:73]
	v_mfma_f32_16x16x32_bf16 v[66:69], v[178:181], v[236:239], v[66:69]
	s_barrier
; #define PG8_STAGE(bufoff, gbase, voff) do { _Pragma("unroll") for (int _i = 0; _i < 2; ++_i) \
;         __builtin_amdgcn_global_load_lds((const unsigned*)((const char*)(gbase) + (voff)[_i]), (PG8_LAS unsigned*)(lds + (bufoff) + ldsw + _i * 8192), 16, 0, PG8_AUX_##voff); } while (0)
; #define PG8_LDA(dst, b, h) do { _Pragma("unroll") for (int m = 0; m < 4; ++m) _Pragma("unroll") for (int k = 0; k < 2; ++k) dst[m][k] = *(const PG8_LAS bf16x8*)(lds + PG8_SA(b, h) + aoff + m * 2048 + k * 1024); } while (0)
; #define PG8_LDB(dst, b, h) do { _Pragma("unroll") for (int n = 0; n < 2; ++n) _Pragma("unroll") for (int k = 0; k < 2; ++k) dst[n][k] = *(const PG8_LAS bf16x8*)(lds + PG8_SB(b, h) + boff + n * 2048 + k * 1024); } while (0)
; #define PG8_WAIT_V(n) asm volatile("s_waitcnt vmcnt(" #n ")" ::: "memory")
; #define PG8_BAR __builtin_amdgcn_s_barrier()
;     ...
;         for (int t = 0; t < nt; t += 2) {
;             const bool last = (t == nt - 2);
;             const char* a1 = cA + (size_t)(t + 1) * kstep;
;             const char* a2 = last ? nA : cA + (size_t)(t + 2) * kstep; const char* b2 = last ? nB : cB + (size_t)(t + 2) * kstep;
;             const char* a3 = a2 + kstep; const char* b3 = b2 + kstep;
;             if (last && has_next) S.a_ready(nxt);
;             if constexpr (SP2) {
;             PG8_LDB(B0, 0, 0); PG8_LDB(B1, 0, 1); PG8_SCHED; PG8_LDA(At, 0, 0); PG8_STAGE(PG8_SA(1, 1), a1 + hstep, voffA);
;             PG8_WAIT_V(8); PG8_WAIT_L(0); PG8_BAR; PG8_MMA(0, 0, At, B0); PG8_MMA(0, 1, At, B1); PG8_BAR; PG8_SCHED;
;             PG8_LDA(At, 0, 1); PG8_STAGE(PG8_SB(0, 0), b2, voffB); PG8_STAGE(PG8_SB(0, 1), b2 + hstep, voffB); PG8_STAGE(PG8_SA(0, 0), a2, voffA);
;             PG8_WAIT_V(8); PG8_WAIT_L(0); PG8_BAR; PG8_MMA(1, 0, At, B0); PG8_MMA(1, 1, At, B1); PG8_BAR; PG8_SCHED;
;             PG8_LDB(B0, 1, 0); PG8_LDB(B1, 1, 1); PG8_SCHED; PG8_LDA(At, 1, 0); PG8_STAGE(PG8_SA(0, 1), a2 + hstep, voffA);
;             PG8_WAIT_V(8); PG8_WAIT_L(0); PG8_BAR; PG8_MMA(0, 0, At, B0); PG8_MMA(0, 1, At, B1); PG8_BAR; PG8_SCHED;
;             PG8_LDA(At, 1, 1); PG8_STAGE(PG8_SB(1, 0), b3, voffB); PG8_STAGE(PG8_SB(1, 1), b3 + hstep, voffB); PG8_STAGE(PG8_SA(1, 0), a3, voffA);
;             PG8_WAIT_V(8); PG8_WAIT_L(0); PG8_BAR; PG8_MMA(1, 0, At, B0); PG8_MMA(1, 1, At, B1); PG8_BAR; PG8_SCHED;
;     ...
;         if constexpr (ALIGN_EPI) { if (wr == 0) PG8_BAR; }
	s_add_i32 s28, s53, s39
	v_lshl_add_u64 v[214:215], v[214:215], 0, s[2:3]
	s_mov_b32 m0, s28
	ds_read_b128 v[182:185], v149 offset:49152
	ds_read_b128 v[186:189], v149 offset:50176
	ds_read_b128 v[190:193], v149 offset:51200
	ds_read_b128 v[200:203], v149 offset:52224
	ds_read_b128 v[204:207], v149 offset:53248
	ds_read_b128 v[208:211], v149 offset:54272
	ds_read_b128 v[232:235], v149 offset:55296
	ds_read_b128 v[236:239], v149 offset:56320
	global_load_lds_dwordx4 v[214:215], off
	s_add_i32 m0, s28, 0x2000
	s_add_u32 s26, s26, 0x160080
	v_lshl_add_u64 v[214:215], v[220:221], 0, s[2:3]
	s_addc_u32 s27, s27, 0
	s_add_i32 s28, s54, s39
	global_load_lds_dwordx4 v[214:215], off
	v_lshl_add_u64 v[214:215], s[26:27], 0, v[194:195]
	s_mov_b32 m0, s28
	s_nop 0
	global_load_lds_dwordx4 v[214:215], off
	v_lshl_add_u64 v[214:215], s[26:27], 0, v[134:135]
	s_add_i32 m0, s28, 0x2000
	s_nop 0
	global_load_lds_dwordx4 v[214:215], off
	v_lshl_add_u64 v[214:215], v[222:223], 0, s[2:3]
	s_mov_b32 m0, s45
	s_nop 0
	global_load_lds_dwordx4 v[214:215], off
	v_lshl_add_u64 v[214:215], v[240:241], 0, s[2:3]
	s_mov_b32 m0, s46
	s_nop 0
	global_load_lds_dwordx4 v[214:215], off
	s_waitcnt vmcnt(8)
	s_waitcnt lgkmcnt(0)
	s_barrier
	v_mfma_f32_16x16x32_bf16 v[62:65], v[150:153], v[182:185], v[62:65]
	v_mfma_f32_16x16x32_bf16 v[58:61], v[158:161], v[182:185], v[58:61]
	v_mfma_f32_16x16x32_bf16 v[46:49], v[150:153], v[190:193], v[46:49]
	v_mfma_f32_16x16x32_bf16 v[42:45], v[158:161], v[190:193], v[42:45]
	v_mfma_f32_16x16x32_bf16 v[30:33], v[150:153], v[204:207], v[30:33]
	v_mfma_f32_16x16x32_bf16 v[26:29], v[158:161], v[204:207], v[26:29]
	v_mfma_f32_16x16x32_bf16 v[14:17], v[150:153], v[232:235], v[14:17]
	v_mfma_f32_16x16x32_bf16 v[10:13], v[158:161], v[232:235], v[10:13]
	v_mfma_f32_16x16x32_bf16 v[62:65], v[154:157], v[186:189], v[62:65]
	v_mfma_f32_16x16x32_bf16 v[58:61], v[162:165], v[186:189], v[58:61]
	v_mfma_f32_16x16x32_bf16 v[46:49], v[154:157], v[200:203], v[46:49]
	v_mfma_f32_16x16x32_bf16 v[42:45], v[162:165], v[200:203], v[42:45]
	v_mfma_f32_16x16x32_bf16 v[30:33], v[154:157], v[208:211], v[30:33]
	v_mfma_f32_16x16x32_bf16 v[26:29], v[162:165], v[208:211], v[26:29]
	v_mfma_f32_16x16x32_bf16 v[14:17], v[154:157], v[236:239], v[14:17]
	v_mfma_f32_16x16x32_bf16 v[10:13], v[162:165], v[236:239], v[10:13]
	v_mfma_f32_16x16x32_bf16 v[54:57], v[166:169], v[182:185], v[54:57]
	v_mfma_f32_16x16x32_bf16 v[50:53], v[174:177], v[182:185], v[50:53]
	v_mfma_f32_16x16x32_bf16 v[38:41], v[166:169], v[190:193], v[38:41]
	v_mfma_f32_16x16x32_bf16 v[34:37], v[174:177], v[190:193], v[34:37]
	v_mfma_f32_16x16x32_bf16 v[22:25], v[166:169], v[204:207], v[22:25]
	v_mfma_f32_16x16x32_bf16 v[18:21], v[174:177], v[204:207], v[18:21]
	v_mfma_f32_16x16x32_bf16 v[6:9], v[166:169], v[232:235], v[6:9]
	v_mfma_f32_16x16x32_bf16 v[2:5], v[174:177], v[232:235], v[2:5]
	v_mfma_f32_16x16x32_bf16 v[54:57], v[170:173], v[186:189], v[54:57]
	v_mfma_f32_16x16x32_bf16 v[50:53], v[178:181], v[186:189], v[50:53]
	v_mfma_f32_16x16x32_bf16 v[38:41], v[170:173], v[200:203], v[38:41]
	v_mfma_f32_16x16x32_bf16 v[34:37], v[178:181], v[200:203], v[34:37]
	v_mfma_f32_16x16x32_bf16 v[22:25], v[170:173], v[208:211], v[22:25]
	v_mfma_f32_16x16x32_bf16 v[18:21], v[178:181], v[208:211], v[18:21]
	v_mfma_f32_16x16x32_bf16 v[6:9], v[170:173], v[236:239], v[6:9]
	v_mfma_f32_16x16x32_bf16 v[2:5], v[178:181], v[236:239], v[2:5]
	s_barrier
	s_add_i32 s26, s17, 2
	s_add_u32 s24, s24, 0x100
	s_addc_u32 s25, s25, 0
	v_lshl_add_u64 v[142:143], v[142:143], 0, s[56:57]
	v_lshl_add_u64 v[140:141], v[140:141], 0, s[56:57]
	s_cmp_ge_i32 s17, s11
	s_mov_b32 s17, s26
	s_cbranch_scc0 .LBB0_809
	s_and_b64 vcc, exec, s[14:15]
	s_cbranch_vccz .LBB0_812
	s_barrier

; #define PG8_STAGE(bufoff, gbase, voff) do { _Pragma("unroll") for (int _i = 0; _i < 2; ++_i) \
;         __builtin_amdgcn_global_load_lds((const unsigned*)((const char*)(gbase) + (voff)[_i]), (PG8_LAS unsigned*)(lds + (bufoff) + ldsw + _i * 8192), 16, 0, PG8_AUX_##voff); } while (0)
; #define PG8_LDA(dst, b, h) do { _Pragma("unroll") for (int m = 0; m < 4; ++m) _Pragma("unroll") for (int k = 0; k < 2; ++k) dst[m][k] = *(const PG8_LAS bf16x8*)(lds + PG8_SA(b, h) + aoff + m * 2048 + k * 1024); } while (0)
; #define PG8_LDB(dst, b, h) do { _Pragma("unroll") for (int n = 0; n < 2; ++n) _Pragma("unroll") for (int k = 0; k < 2; ++k) dst[n][k] = *(const PG8_LAS bf16x8*)(lds + PG8_SB(b, h) + boff + n * 2048 + k * 1024); } while (0)
; #define PG8_MMA(ai, bj, At, Bt) do { __builtin_amdgcn_s_setprio(1); _Pragma("unroll") for (int m = 0; m < 4; ++m) _Pragma("unroll") for (int n = 0; n < 2; ++n) _Pragma("unroll") for (int k = 0; k < 2; ++k) \
;         acc[ai][bj][m][n] = __builtin_amdgcn_mfma_f32_16x16x32_bf16(Bt[n][k], At[m][k], acc[ai][bj][m][n], 0, 0, 0); __builtin_amdgcn_s_setprio(0); } while (0)
; #define PG8_WAIT_V(n) asm volatile("s_waitcnt vmcnt(" #n ")" ::: "memory")
; #define PG8_WAIT_L(n) asm volatile("s_waitcnt lgkmcnt(" #n ")" ::: "memory")
; #define PG8_BAR __builtin_amdgcn_s_barrier()
; #define PG8_SCHED __builtin_amdgcn_sched_barrier(0)
;     ...
;         for (int t = 0; t < nt; t += 2) {
;             const bool last = (t == nt - 2);
;             const char* a1 = cA + (size_t)(t + 1) * kstep;
;             const char* a2 = last ? nA : cA + (size_t)(t + 2) * kstep; const char* b2 = last ? nB : cB + (size_t)(t + 2) * kstep;
;             const char* a3 = a2 + kstep; const char* b3 = b2 + kstep;
;             if (last && has_next) S.a_ready(nxt);
;             if constexpr (SP2) {
;             PG8_LDB(B0, 0, 0); PG8_LDB(B1, 0, 1); PG8_SCHED; PG8_LDA(At, 0, 0); PG8_STAGE(PG8_SA(1, 1), a1 + hstep, voffA);
;             PG8_WAIT_V(8); PG8_WAIT_L(0); PG8_BAR; PG8_MMA(0, 0, At, B0); PG8_MMA(0, 1, At, B1); PG8_BAR; PG8_SCHED;
;             PG8_LDA(At, 0, 1); PG8_STAGE(PG8_SB(0, 0), b2, voffB); PG8_STAGE(PG8_SB(0, 1), b2 + hstep, voffB); PG8_STAGE(PG8_SA(0, 0), a2, voffA);
;             PG8_WAIT_V(8); PG8_WAIT_L(0); PG8_BAR; PG8_MMA(1, 0, At, B0); PG8_MMA(1, 1, At, B1); PG8_BAR; PG8_SCHED;
.LBB0_1097:
	s_lshl_b32 s28, s57, 7
	s_add_u32 s34, s12, s28
	s_addc_u32 s35, s13, 0
	s_add_i32 s31, s57, 2
	s_lshl_b32 s36, s31, 7
	s_add_u32 s37, s12, s36
	s_addc_u32 s58, s13, 0
	s_and_b64 s[28:29], s[26:27], exec
	s_cselect_b32 s29, s11, s58
	s_cselect_b32 s28, s54, s37
	s_add_u32 s36, s4, s36
	s_addc_u32 s37, s5, 0
	s_and_b64 s[26:27], s[26:27], exec
	s_cselect_b32 s27, s15, s37
	s_cselect_b32 s26, s55, s36
	s_add_i32 s36, 0, 0x10000
	v_add_u32_e32 v138, s36, v142
	s_add_i32 s37, 0, 0x14000
	ds_read_b128 v[146:149], v138
	ds_read_b128 v[150:153], v138 offset:1024
	ds_read_b128 v[154:157], v138 offset:2048
	ds_read_b128 v[158:161], v138 offset:3072
	v_add_u32_e32 v138, s37, v142
	ds_read_b128 v[162:165], v138
	ds_read_b128 v[166:169], v138 offset:1024
	ds_read_b128 v[170:173], v138 offset:2048
	ds_read_b128 v[174:177], v138 offset:3072
	s_add_u32 s34, s34, 0x80080
	s_addc_u32 s35, s35, 0
	v_lshl_add_u64 v[138:139], s[34:35], 0, v[130:131]
	s_add_i32 m0, s44, 0xc000
	ds_read_b128 v[178:181], v144
	ds_read_b128 v[182:185], v144 offset:1024
	ds_read_b128 v[186:189], v144 offset:2048
	ds_read_b128 v[190:193], v144 offset:3072
	ds_read_b128 v[200:203], v144 offset:4096
	ds_read_b128 v[204:207], v144 offset:5120
	ds_read_b128 v[208:211], v144 offset:6144
	ds_read_b128 v[212:215], v144 offset:7168
	global_load_lds_dwordx4 v[138:139], off
	v_lshl_add_u64 v[138:139], s[34:35], 0, v[134:135]
	s_add_i32 m0, s44, 0xe000
	s_nop 0
	global_load_lds_dwordx4 v[138:139], off
	s_waitcnt vmcnt(8)
	s_waitcnt lgkmcnt(0)
	s_barrier
	v_mfma_f32_16x16x32_bf16 v[126:129], v[146:149], v[178:181], v[126:129]
	v_mfma_f32_16x16x32_bf16 v[122:125], v[154:157], v[178:181], v[122:125]
	v_mfma_f32_16x16x32_bf16 v[118:121], v[146:149], v[186:189], v[118:121]
	v_mfma_f32_16x16x32_bf16 v[114:117], v[154:157], v[186:189], v[114:117]
	v_mfma_f32_16x16x32_bf16 v[110:113], v[146:149], v[200:203], v[110:113]
	v_mfma_f32_16x16x32_bf16 v[106:109], v[154:157], v[200:203], v[106:109]
	v_mfma_f32_16x16x32_bf16 v[102:105], v[146:149], v[208:211], v[102:105]
	v_mfma_f32_16x16x32_bf16 v[98:101], v[154:157], v[208:211], v[98:101]
	v_mfma_f32_16x16x32_bf16 v[126:129], v[150:153], v[182:185], v[126:129]
	v_mfma_f32_16x16x32_bf16 v[122:125], v[158:161], v[182:185], v[122:125]
	v_mfma_f32_16x16x32_bf16 v[118:121], v[150:153], v[190:193], v[118:121]
	v_mfma_f32_16x16x32_bf16 v[114:117], v[158:161], v[190:193], v[114:117]
	v_mfma_f32_16x16x32_bf16 v[110:113], v[150:153], v[204:207], v[110:113]
	v_mfma_f32_16x16x32_bf16 v[106:109], v[158:161], v[204:207], v[106:109]
	v_mfma_f32_16x16x32_bf16 v[102:105], v[150:153], v[212:215], v[102:105]
	v_mfma_f32_16x16x32_bf16 v[98:101], v[158:161], v[212:215], v[98:101]
	v_mfma_f32_16x16x32_bf16 v[94:97], v[162:165], v[178:181], v[94:97]
	v_mfma_f32_16x16x32_bf16 v[90:93], v[170:173], v[178:181], v[90:93]
	v_mfma_f32_16x16x32_bf16 v[86:89], v[162:165], v[186:189], v[86:89]
	v_mfma_f32_16x16x32_bf16 v[82:85], v[170:173], v[186:189], v[82:85]
	v_mfma_f32_16x16x32_bf16 v[78:81], v[162:165], v[200:203], v[78:81]
	v_mfma_f32_16x16x32_bf16 v[74:77], v[170:173], v[200:203], v[74:77]
	v_mfma_f32_16x16x32_bf16 v[70:73], v[162:165], v[208:211], v[70:73]
	v_mfma_f32_16x16x32_bf16 v[66:69], v[170:173], v[208:211], v[66:69]
	v_mfma_f32_16x16x32_bf16 v[94:97], v[166:169], v[182:185], v[94:97]
	v_mfma_f32_16x16x32_bf16 v[90:93], v[174:177], v[182:185], v[90:93]
	v_mfma_f32_16x16x32_bf16 v[86:89], v[166:169], v[190:193], v[86:89]
	v_mfma_f32_16x16x32_bf16 v[82:85], v[174:177], v[190:193], v[82:85]
	v_mfma_f32_16x16x32_bf16 v[78:81], v[166:169], v[204:207], v[78:81]
	v_mfma_f32_16x16x32_bf16 v[74:77], v[174:177], v[204:207], v[74:77]
	v_mfma_f32_16x16x32_bf16 v[70:73], v[166:169], v[212:215], v[70:73]
	v_mfma_f32_16x16x32_bf16 v[66:69], v[174:177], v[212:215], v[66:69]
	s_barrier
	s_add_i32 s34, s36, s43
	v_lshl_add_u64 v[138:139], s[26:27], 0, v[132:133]
	s_mov_b32 m0, s34
	ds_read_b128 v[178:181], v144 offset:16384
	ds_read_b128 v[182:185], v144 offset:17408
	ds_read_b128 v[186:189], v144 offset:18432
	ds_read_b128 v[190:193], v144 offset:19456
	ds_read_b128 v[200:203], v144 offset:20480
	ds_read_b128 v[204:207], v144 offset:21504
	ds_read_b128 v[208:211], v144 offset:22528
	ds_read_b128 v[212:215], v144 offset:23552
	global_load_lds_dwordx4 v[138:139], off
	s_add_i32 m0, s34, 0x2000
	s_add_u32 s34, s26, 0x80000
	v_lshl_add_u64 v[220:221], s[26:27], 0, v[136:137]
	s_addc_u32 s35, s27, 0
	s_add_i32 s36, s37, s43
	global_load_lds_dwordx4 v[220:221], off
	v_lshl_add_u64 v[222:223], s[34:35], 0, v[132:133]
	s_mov_b32 m0, s36
	v_lshl_add_u64 v[230:231], s[28:29], 0, v[134:135]
	global_load_lds_dwordx4 v[222:223], off
	v_lshl_add_u64 v[222:223], s[34:35], 0, v[136:137]
	s_add_i32 m0, s36, 0x2000
	s_nop 0
	global_load_lds_dwordx4 v[222:223], off
	v_lshl_add_u64 v[222:223], s[28:29], 0, v[130:131]
	s_mov_b32 m0, s44
	s_nop 0
	global_load_lds_dwordx4 v[222:223], off
	s_mov_b32 m0, s45
	s_nop 0
	global_load_lds_dwordx4 v[230:231], off
	s_waitcnt vmcnt(8)
	s_waitcnt lgkmcnt(0)
	s_barrier
; #define PG8_STAGE(bufoff, gbase, voff) do { _Pragma("unroll") for (int _i = 0; _i < 2; ++_i) \
;         __builtin_amdgcn_global_load_lds((const unsigned*)((const char*)(gbase) + (voff)[_i]), (PG8_LAS unsigned*)(lds + (bufoff) + ldsw + _i * 8192), 16, 0, PG8_AUX_##voff); } while (0)
; #define PG8_LDA(dst, b, h) do { _Pragma("unroll") for (int m = 0; m < 4; ++m) _Pragma("unroll") for (int k = 0; k < 2; ++k) dst[m][k] = *(const PG8_LAS bf16x8*)(lds + PG8_SA(b, h) + aoff + m * 2048 + k * 1024); } while (0)
; #define PG8_LDB(dst, b, h) do { _Pragma("unroll") for (int n = 0; n < 2; ++n) _Pragma("unroll") for (int k = 0; k < 2; ++k) dst[n][k] = *(const PG8_LAS bf16x8*)(lds + PG8_SB(b, h) + boff + n * 2048 + k * 1024); } while (0)
; #define PG8_MMA(ai, bj, At, Bt) do { __builtin_amdgcn_s_setprio(1); _Pragma("unroll") for (int m = 0; m < 4; ++m) _Pragma("unroll") for (int n = 0; n < 2; ++n) _Pragma("unroll") for (int k = 0; k < 2; ++k) \
;         acc[ai][bj][m][n] = __builtin_amdgcn_mfma_f32_16x16x32_bf16(Bt[n][k], At[m][k], acc[ai][bj][m][n], 0, 0, 0); __builtin_amdgcn_s_setprio(0); } while (0)
; #define PG8_WAIT_V(n) asm volatile("s_waitcnt vmcnt(" #n ")" ::: "memory")
; #define PG8_WAIT_L(n) asm volatile("s_waitcnt lgkmcnt(" #n ")" ::: "memory")
; #define PG8_BAR __builtin_amdgcn_s_barrier()
; #define PG8_SCHED __builtin_amdgcn_sched_barrier(0)
;     ...
;             PG8_WAIT_V(8); PG8_WAIT_L(0); PG8_BAR; PG8_MMA(1, 0, At, B0); PG8_MMA(1, 1, At, B1); PG8_BAR; PG8_SCHED;
;             PG8_LDB(B0, 1, 0); PG8_LDB(B1, 1, 1); PG8_SCHED; PG8_LDA(At, 1, 0); PG8_STAGE(PG8_SA(0, 1), a2 + hstep, voffA);
;             PG8_WAIT_V(8); PG8_WAIT_L(0); PG8_BAR; PG8_MMA(0, 0, At, B0); PG8_MMA(0, 1, At, B1); PG8_BAR; PG8_SCHED;
	v_mfma_f32_16x16x32_bf16 v[62:65], v[146:149], v[178:181], v[62:65]
	v_mfma_f32_16x16x32_bf16 v[58:61], v[154:157], v[178:181], v[58:61]
	v_mfma_f32_16x16x32_bf16 v[54:57], v[146:149], v[186:189], v[54:57]
	v_mfma_f32_16x16x32_bf16 v[50:53], v[154:157], v[186:189], v[50:53]
	v_mfma_f32_16x16x32_bf16 v[46:49], v[146:149], v[200:203], v[46:49]
	v_mfma_f32_16x16x32_bf16 v[42:45], v[154:157], v[200:203], v[42:45]
	v_mfma_f32_16x16x32_bf16 v[38:41], v[146:149], v[208:211], v[38:41]
	v_mfma_f32_16x16x32_bf16 v[34:37], v[154:157], v[208:211], v[34:37]
	v_mfma_f32_16x16x32_bf16 v[62:65], v[150:153], v[182:185], v[62:65]
	v_mfma_f32_16x16x32_bf16 v[58:61], v[158:161], v[182:185], v[58:61]
	v_mfma_f32_16x16x32_bf16 v[54:57], v[150:153], v[190:193], v[54:57]
	v_mfma_f32_16x16x32_bf16 v[50:53], v[158:161], v[190:193], v[50:53]
	v_mfma_f32_16x16x32_bf16 v[46:49], v[150:153], v[204:207], v[46:49]
	v_mfma_f32_16x16x32_bf16 v[42:45], v[158:161], v[204:207], v[42:45]
	v_mfma_f32_16x16x32_bf16 v[38:41], v[150:153], v[212:215], v[38:41]
	v_mfma_f32_16x16x32_bf16 v[34:37], v[158:161], v[212:215], v[34:37]
	v_mfma_f32_16x16x32_bf16 v[30:33], v[162:165], v[178:181], v[30:33]
	v_mfma_f32_16x16x32_bf16 v[26:29], v[170:173], v[178:181], v[26:29]
	v_mfma_f32_16x16x32_bf16 v[22:25], v[162:165], v[186:189], v[22:25]
	v_mfma_f32_16x16x32_bf16 v[18:21], v[170:173], v[186:189], v[18:21]
	v_mfma_f32_16x16x32_bf16 v[14:17], v[162:165], v[200:203], v[14:17]
	v_mfma_f32_16x16x32_bf16 v[10:13], v[170:173], v[200:203], v[10:13]
	v_mfma_f32_16x16x32_bf16 v[6:9], v[162:165], v[208:211], v[6:9]
	v_mfma_f32_16x16x32_bf16 v[2:5], v[170:173], v[208:211], v[2:5]
	v_mfma_f32_16x16x32_bf16 v[30:33], v[166:169], v[182:185], v[30:33]
	v_mfma_f32_16x16x32_bf16 v[26:29], v[174:177], v[182:185], v[26:29]
	v_mfma_f32_16x16x32_bf16 v[22:25], v[166:169], v[190:193], v[22:25]
	v_mfma_f32_16x16x32_bf16 v[18:21], v[174:177], v[190:193], v[18:21]
	v_mfma_f32_16x16x32_bf16 v[14:17], v[166:169], v[204:207], v[14:17]
	v_mfma_f32_16x16x32_bf16 v[10:13], v[174:177], v[204:207], v[10:13]
	v_mfma_f32_16x16x32_bf16 v[6:9], v[166:169], v[212:215], v[6:9]
	v_mfma_f32_16x16x32_bf16 v[2:5], v[174:177], v[212:215], v[2:5]
	s_barrier
	s_add_i32 s34, 0, 0x18000
	v_add_u32_e32 v145, s34, v142
	s_add_i32 s35, 0, 0x1c000
	ds_read_b128 v[146:149], v145
	ds_read_b128 v[150:153], v145 offset:1024
	ds_read_b128 v[154:157], v145 offset:2048
	ds_read_b128 v[158:161], v145 offset:3072
	v_add_u32_e32 v145, s35, v142
	ds_read_b128 v[162:165], v145
	ds_read_b128 v[166:169], v145 offset:1024
	ds_read_b128 v[170:173], v145 offset:2048
	ds_read_b128 v[174:177], v145 offset:3072
	s_add_u32 s28, s28, 0x80000
	s_addc_u32 s29, s29, 0
	s_mov_b32 m0, s46
	v_lshl_add_u64 v[232:233], s[28:29], 0, v[130:131]
	ds_read_b128 v[178:181], v144 offset:32768
	ds_read_b128 v[182:185], v144 offset:33792
	ds_read_b128 v[186:189], v144 offset:34816
	ds_read_b128 v[190:193], v144 offset:35840
	ds_read_b128 v[200:203], v144 offset:36864
	ds_read_b128 v[204:207], v144 offset:37888
	ds_read_b128 v[208:211], v144 offset:38912
	ds_read_b128 v[212:215], v144 offset:39936
	global_load_lds_dwordx4 v[232:233], off
	v_lshl_add_u64 v[232:233], s[28:29], 0, v[134:135]
	s_mov_b32 m0, s47
	s_nop 0
	global_load_lds_dwordx4 v[232:233], off
	s_waitcnt vmcnt(8)
	s_waitcnt lgkmcnt(0)
	s_barrier
	v_mfma_f32_16x16x32_bf16 v[126:129], v[146:149], v[178:181], v[126:129]
	v_mfma_f32_16x16x32_bf16 v[122:125], v[154:157], v[178:181], v[122:125]
	v_mfma_f32_16x16x32_bf16 v[118:121], v[146:149], v[186:189], v[118:121]
	v_mfma_f32_16x16x32_bf16 v[114:117], v[154:157], v[186:189], v[114:117]
	v_mfma_f32_16x16x32_bf16 v[110:113], v[146:149], v[200:203], v[110:113]
	v_mfma_f32_16x16x32_bf16 v[106:109], v[154:157], v[200:203], v[106:109]
	v_mfma_f32_16x16x32_bf16 v[102:105], v[146:149], v[208:211], v[102:105]
	v_mfma_f32_16x16x32_bf16 v[98:101], v[154:157], v[208:211], v[98:101]
	v_mfma_f32_16x16x32_bf16 v[126:129], v[150:153], v[182:185], v[126:129]
	v_mfma_f32_16x16x32_bf16 v[122:125], v[158:161], v[182:185], v[122:125]
	v_mfma_f32_16x16x32_bf16 v[118:121], v[150:153], v[190:193], v[118:121]
	v_mfma_f32_16x16x32_bf16 v[114:117], v[158:161], v[190:193], v[114:117]
	v_mfma_f32_16x16x32_bf16 v[110:113], v[150:153], v[204:207], v[110:113]
	v_mfma_f32_16x16x32_bf16 v[106:109], v[158:161], v[204:207], v[106:109]
	v_mfma_f32_16x16x32_bf16 v[102:105], v[150:153], v[212:215], v[102:105]
	v_mfma_f32_16x16x32_bf16 v[98:101], v[158:161], v[212:215], v[98:101]
	v_mfma_f32_16x16x32_bf16 v[94:97], v[162:165], v[178:181], v[94:97]
	v_mfma_f32_16x16x32_bf16 v[90:93], v[170:173], v[178:181], v[90:93]
	v_mfma_f32_16x16x32_bf16 v[86:89], v[162:165], v[186:189], v[86:89]
	v_mfma_f32_16x16x32_bf16 v[82:85], v[170:173], v[186:189], v[82:85]
	v_mfma_f32_16x16x32_bf16 v[78:81], v[162:165], v[200:203], v[78:81]
	v_mfma_f32_16x16x32_bf16 v[74:77], v[170:173], v[200:203], v[74:77]
	v_mfma_f32_16x16x32_bf16 v[70:73], v[162:165], v[208:211], v[70:73]
	v_mfma_f32_16x16x32_bf16 v[66:69], v[170:173], v[208:211], v[66:69]
	v_mfma_f32_16x16x32_bf16 v[94:97], v[166:169], v[182:185], v[94:97]
	v_mfma_f32_16x16x32_bf16 v[90:93], v[174:177], v[182:185], v[90:93]
	v_mfma_f32_16x16x32_bf16 v[86:89], v[166:169], v[190:193], v[86:89]
	v_mfma_f32_16x16x32_bf16 v[82:85], v[174:177], v[190:193], v[82:85]
	v_mfma_f32_16x16x32_bf16 v[78:81], v[166:169], v[204:207], v[78:81]
	v_mfma_f32_16x16x32_bf16 v[74:77], v[174:177], v[204:207], v[74:77]
	v_mfma_f32_16x16x32_bf16 v[70:73], v[166:169], v[212:215], v[70:73]
	v_mfma_f32_16x16x32_bf16 v[66:69], v[174:177], v[212:215], v[66:69]
	s_barrier
; #define PG8_STAGE(bufoff, gbase, voff) do { _Pragma("unroll") for (int _i = 0; _i < 2; ++_i) \
;         __builtin_amdgcn_global_load_lds((const unsigned*)((const char*)(gbase) + (voff)[_i]), (PG8_LAS unsigned*)(lds + (bufoff) + ldsw + _i * 8192), 16, 0, PG8_AUX_##voff); } while (0)
; #define PG8_LDA(dst, b, h) do { _Pragma("unroll") for (int m = 0; m < 4; ++m) _Pragma("unroll") for (int k = 0; k < 2; ++k) dst[m][k] = *(const PG8_LAS bf16x8*)(lds + PG8_SA(b, h) + aoff + m * 2048 + k * 1024); } while (0)
; #define PG8_LDB(dst, b, h) do { _Pragma("unroll") for (int n = 0; n < 2; ++n) _Pragma("unroll") for (int k = 0; k < 2; ++k) dst[n][k] = *(const PG8_LAS bf16x8*)(lds + PG8_SB(b, h) + boff + n * 2048 + k * 1024); } while (0)
; #define PG8_WAIT_V(n) asm volatile("s_waitcnt vmcnt(" #n ")" ::: "memory")
; #define PG8_WAIT_L(n) asm volatile("s_waitcnt lgkmcnt(" #n ")" ::: "memory")
;     ...
;         for (int t = 0; t < nt; t += 2) {
;             const bool last = (t == nt - 2);
;             const char* a1 = cA + (size_t)(t + 1) * kstep;
;             const char* a2 = last ? nA : cA + (size_t)(t + 2) * kstep; const char* b2 = last ? nB : cB + (size_t)(t + 2) * kstep;
;             const char* a3 = a2 + kstep; const char* b3 = b2 + kstep;
;             if (last && has_next) S.a_ready(nxt);
;             if constexpr (SP2) {
;             PG8_LDB(B0, 0, 0); PG8_LDB(B1, 0, 1); PG8_SCHED; PG8_LDA(At, 0, 0); PG8_STAGE(PG8_SA(1, 1), a1 + hstep, voffA);
;             PG8_WAIT_V(8); PG8_WAIT_L(0); PG8_BAR; PG8_MMA(0, 0, At, B0); PG8_MMA(0, 1, At, B1); PG8_BAR; PG8_SCHED;
;             PG8_LDA(At, 0, 1); PG8_STAGE(PG8_SB(0, 0), b2, voffB); PG8_STAGE(PG8_SB(0, 1), b2 + hstep, voffB); PG8_STAGE(PG8_SA(0, 0), a2, voffA);
;             PG8_WAIT_V(8); PG8_WAIT_L(0); PG8_BAR; PG8_MMA(1, 0, At, B0); PG8_MMA(1, 1, At, B1); PG8_BAR; PG8_SCHED;
;             PG8_LDB(B0, 1, 0); PG8_LDB(B1, 1, 1); PG8_SCHED; PG8_LDA(At, 1, 0); PG8_STAGE(PG8_SA(0, 1), a2 + hstep, voffA);
;             PG8_WAIT_V(8); PG8_WAIT_L(0); PG8_BAR; PG8_MMA(0, 0, At, B0); PG8_MMA(0, 1, At, B1); PG8_BAR; PG8_SCHED;
;             PG8_LDA(At, 1, 1); PG8_STAGE(PG8_SB(1, 0), b3, voffB); PG8_STAGE(PG8_SB(1, 1), b3 + hstep, voffB); PG8_STAGE(PG8_SA(1, 0), a3, voffA);
;             PG8_WAIT_V(8); PG8_WAIT_L(0); PG8_BAR; PG8_MMA(1, 0, At, B0); PG8_MMA(1, 1, At, B1); PG8_BAR; PG8_SCHED;
	s_add_i32 s28, s34, s43
	v_lshl_add_u64 v[138:139], v[138:139], 0, s[2:3]
	s_mov_b32 m0, s28
	ds_read_b128 v[178:181], v144 offset:49152
	ds_read_b128 v[182:185], v144 offset:50176
	ds_read_b128 v[186:189], v144 offset:51200
	ds_read_b128 v[190:193], v144 offset:52224
	ds_read_b128 v[200:203], v144 offset:53248
	ds_read_b128 v[204:207], v144 offset:54272
	ds_read_b128 v[208:211], v144 offset:55296
	ds_read_b128 v[212:215], v144 offset:56320
	global_load_lds_dwordx4 v[138:139], off
	s_add_i32 m0, s28, 0x2000
	s_add_u32 s26, s26, 0x80080
	v_lshl_add_u64 v[138:139], v[220:221], 0, s[2:3]
	s_addc_u32 s27, s27, 0
	s_add_i32 s28, s35, s43
	global_load_lds_dwordx4 v[138:139], off
	v_lshl_add_u64 v[138:139], s[26:27], 0, v[132:133]
	s_mov_b32 m0, s28
	s_nop 0
	global_load_lds_dwordx4 v[138:139], off
	v_lshl_add_u64 v[138:139], s[26:27], 0, v[136:137]
	s_add_i32 m0, s28, 0x2000
	s_nop 0
	global_load_lds_dwordx4 v[138:139], off
	v_lshl_add_u64 v[138:139], v[222:223], 0, s[2:3]
	s_mov_b32 m0, s48
	s_nop 0
	global_load_lds_dwordx4 v[138:139], off
	v_lshl_add_u64 v[138:139], v[230:231], 0, s[2:3]
	s_mov_b32 m0, s49
	s_nop 0
	global_load_lds_dwordx4 v[138:139], off
	s_waitcnt vmcnt(8)
	s_waitcnt lgkmcnt(0)
	s_barrier
	v_mfma_f32_16x16x32_bf16 v[62:65], v[146:149], v[178:181], v[62:65]
	v_mfma_f32_16x16x32_bf16 v[58:61], v[154:157], v[178:181], v[58:61]
	v_mfma_f32_16x16x32_bf16 v[54:57], v[146:149], v[186:189], v[54:57]
	v_mfma_f32_16x16x32_bf16 v[50:53], v[154:157], v[186:189], v[50:53]
	v_mfma_f32_16x16x32_bf16 v[46:49], v[146:149], v[200:203], v[46:49]
	v_mfma_f32_16x16x32_bf16 v[42:45], v[154:157], v[200:203], v[42:45]
	v_mfma_f32_16x16x32_bf16 v[38:41], v[146:149], v[208:211], v[38:41]
	v_mfma_f32_16x16x32_bf16 v[34:37], v[154:157], v[208:211], v[34:37]
	v_mfma_f32_16x16x32_bf16 v[62:65], v[150:153], v[182:185], v[62:65]
	v_mfma_f32_16x16x32_bf16 v[58:61], v[158:161], v[182:185], v[58:61]
	v_mfma_f32_16x16x32_bf16 v[54:57], v[150:153], v[190:193], v[54:57]
	v_mfma_f32_16x16x32_bf16 v[50:53], v[158:161], v[190:193], v[50:53]
	v_mfma_f32_16x16x32_bf16 v[46:49], v[150:153], v[204:207], v[46:49]
	v_mfma_f32_16x16x32_bf16 v[42:45], v[158:161], v[204:207], v[42:45]
	v_mfma_f32_16x16x32_bf16 v[38:41], v[150:153], v[212:215], v[38:41]
	v_mfma_f32_16x16x32_bf16 v[34:37], v[158:161], v[212:215], v[34:37]
	v_mfma_f32_16x16x32_bf16 v[30:33], v[162:165], v[178:181], v[30:33]
	v_mfma_f32_16x16x32_bf16 v[26:29], v[170:173], v[178:181], v[26:29]
	v_mfma_f32_16x16x32_bf16 v[22:25], v[162:165], v[186:189], v[22:25]
	v_mfma_f32_16x16x32_bf16 v[18:21], v[170:173], v[186:189], v[18:21]
	v_mfma_f32_16x16x32_bf16 v[14:17], v[162:165], v[200:203], v[14:17]
	v_mfma_f32_16x16x32_bf16 v[10:13], v[170:173], v[200:203], v[10:13]
	v_mfma_f32_16x16x32_bf16 v[6:9], v[162:165], v[208:211], v[6:9]
	v_mfma_f32_16x16x32_bf16 v[2:5], v[170:173], v[208:211], v[2:5]
	v_mfma_f32_16x16x32_bf16 v[30:33], v[166:169], v[182:185], v[30:33]
	v_mfma_f32_16x16x32_bf16 v[26:29], v[174:177], v[182:185], v[26:29]
	v_mfma_f32_16x16x32_bf16 v[22:25], v[166:169], v[190:193], v[22:25]
	v_mfma_f32_16x16x32_bf16 v[18:21], v[174:177], v[190:193], v[18:21]
	v_mfma_f32_16x16x32_bf16 v[14:17], v[166:169], v[204:207], v[14:17]
	v_mfma_f32_16x16x32_bf16 v[10:13], v[174:177], v[204:207], v[10:13]
	v_mfma_f32_16x16x32_bf16 v[6:9], v[166:169], v[212:215], v[6:9]
	v_mfma_f32_16x16x32_bf16 v[2:5], v[174:177], v[212:215], v[2:5]
	s_barrier
	s_cmp_gt_u32 s57, 29
	s_cbranch_scc1 .LBB0_1099
	s_mov_b32 s57, s31
	s_branch .LBB0_1080

; #define PG8_STAGE(bufoff, gbase, voff) do { _Pragma("unroll") for (int _i = 0; _i < 2; ++_i) \
;         __builtin_amdgcn_global_load_lds((const unsigned*)((const char*)(gbase) + (voff)[_i]), (PG8_LAS unsigned*)(lds + (bufoff) + ldsw + _i * 8192), 16, 0, PG8_AUX_##voff); } while (0)
; #define PG8_LDA(dst, b, h) do { _Pragma("unroll") for (int m = 0; m < 4; ++m) _Pragma("unroll") for (int k = 0; k < 2; ++k) dst[m][k] = *(const PG8_LAS bf16x8*)(lds + PG8_SA(b, h) + aoff + m * 2048 + k * 1024); } while (0)
; #define PG8_LDB(dst, b, h) do { _Pragma("unroll") for (int n = 0; n < 2; ++n) _Pragma("unroll") for (int k = 0; k < 2; ++k) dst[n][k] = *(const PG8_LAS bf16x8*)(lds + PG8_SB(b, h) + boff + n * 2048 + k * 1024); } while (0)
; #define PG8_MMA(ai, bj, At, Bt) do { __builtin_amdgcn_s_setprio(1); _Pragma("unroll") for (int m = 0; m < 4; ++m) _Pragma("unroll") for (int n = 0; n < 2; ++n) _Pragma("unroll") for (int k = 0; k < 2; ++k) \
;         acc[ai][bj][m][n] = __builtin_amdgcn_mfma_f32_16x16x32_bf16(Bt[n][k], At[m][k], acc[ai][bj][m][n], 0, 0, 0); __builtin_amdgcn_s_setprio(0); } while (0)
; #define PG8_WAIT_V(n) asm volatile("s_waitcnt vmcnt(" #n ")" ::: "memory")
; #define PG8_WAIT_L(n) asm volatile("s_waitcnt lgkmcnt(" #n ")" ::: "memory")
; #define PG8_BAR __builtin_amdgcn_s_barrier()
; #define PG8_SCHED __builtin_amdgcn_sched_barrier(0)
;     ...
;         for (int t = 0; t < nt; t += 2) {
;             const bool last = (t == nt - 2);
;             const char* a1 = cA + (size_t)(t + 1) * kstep;
;             const char* a2 = last ? nA : cA + (size_t)(t + 2) * kstep; const char* b2 = last ? nB : cB + (size_t)(t + 2) * kstep;
;             const char* a3 = a2 + kstep; const char* b3 = b2 + kstep;
;             if (last && has_next) S.a_ready(nxt);
;             if constexpr (SP2) {
;             PG8_LDB(B0, 0, 0); PG8_LDB(B1, 0, 1); PG8_SCHED; PG8_LDA(At, 0, 0); PG8_STAGE(PG8_SA(1, 1), a1 + hstep, voffA);
;             PG8_WAIT_V(8); PG8_WAIT_L(0); PG8_BAR; PG8_MMA(0, 0, At, B0); PG8_MMA(0, 1, At, B1); PG8_BAR; PG8_SCHED;
;             PG8_LDA(At, 0, 1); PG8_STAGE(PG8_SB(0, 0), b2, voffB); PG8_STAGE(PG8_SB(0, 1), b2 + hstep, voffB); PG8_STAGE(PG8_SA(0, 0), a2, voffA);
;             PG8_WAIT_V(8); PG8_WAIT_L(0); PG8_BAR; PG8_MMA(1, 0, At, B0); PG8_MMA(1, 1, At, B1); PG8_BAR; PG8_SCHED;
.LBB0_1797:
	s_add_u32 s36, s28, s34
	s_addc_u32 s37, s29, s35
	s_add_u32 s60, s26, s34
	s_addc_u32 s61, s27, s35
	s_add_i32 s62, 0, 0x10000
	s_cmp_eq_u32 s13, s59
	s_cselect_b32 s39, s15, s37
	s_cselect_b32 s38, s19, s36
	s_cselect_b32 s37, s17, s61
	s_cselect_b32 s36, s58, s60
	s_add_i32 s63, 0, 0x14000
	v_add_u32_e32 v162, s62, v146
	v_add_u32_e32 v178, s63, v146
	ds_read_b128 v[150:153], v162
	ds_read_b128 v[154:157], v162 offset:1024
	ds_read_b128 v[158:161], v162 offset:2048
	ds_read_b128 v[162:165], v162 offset:3072
	ds_read_b128 v[166:169], v178
	ds_read_b128 v[170:173], v178 offset:1024
	ds_read_b128 v[174:177], v178 offset:2048
	ds_read_b128 v[178:181], v178 offset:3072
	v_lshl_add_u64 v[192:193], s[28:29], 0, v[142:143]
	s_add_i32 m0, s1, 0xc000
	ds_read_b128 v[182:185], v149
	ds_read_b128 v[188:191], v149 offset:1024
	ds_read_b128 v[200:203], v149 offset:2048
	ds_read_b128 v[204:207], v149 offset:3072
	ds_read_b128 v[208:211], v149 offset:4096
	ds_read_b128 v[212:215], v149 offset:5120
	ds_read_b128 v[220:223], v149 offset:6144
	ds_read_b128 v[230:233], v149 offset:7168
	global_load_lds_dwordx4 v[192:193], off
	v_lshl_add_u64 v[192:193], s[28:29], 0, v[140:141]
	s_add_i32 m0, s1, 0xe000
	s_nop 0
	global_load_lds_dwordx4 v[192:193], off
	s_waitcnt vmcnt(8)
	s_waitcnt lgkmcnt(0)
	s_barrier
	v_mfma_f32_16x16x32_bf16 v[122:125], v[150:153], v[182:185], v[122:125]
	v_mfma_f32_16x16x32_bf16 v[126:129], v[158:161], v[182:185], v[126:129]
	v_mfma_f32_16x16x32_bf16 v[110:113], v[150:153], v[200:203], v[110:113]
	v_mfma_f32_16x16x32_bf16 v[106:109], v[158:161], v[200:203], v[106:109]
	v_mfma_f32_16x16x32_bf16 v[94:97], v[150:153], v[208:211], v[94:97]
	v_mfma_f32_16x16x32_bf16 v[90:93], v[158:161], v[208:211], v[90:93]
	v_mfma_f32_16x16x32_bf16 v[78:81], v[150:153], v[220:223], v[78:81]
	v_mfma_f32_16x16x32_bf16 v[74:77], v[158:161], v[220:223], v[74:77]
	v_mfma_f32_16x16x32_bf16 v[122:125], v[154:157], v[188:191], v[122:125]
	v_mfma_f32_16x16x32_bf16 v[126:129], v[162:165], v[188:191], v[126:129]
	v_mfma_f32_16x16x32_bf16 v[110:113], v[154:157], v[204:207], v[110:113]
	v_mfma_f32_16x16x32_bf16 v[106:109], v[162:165], v[204:207], v[106:109]
	v_mfma_f32_16x16x32_bf16 v[94:97], v[154:157], v[212:215], v[94:97]
	v_mfma_f32_16x16x32_bf16 v[90:93], v[162:165], v[212:215], v[90:93]
	v_mfma_f32_16x16x32_bf16 v[78:81], v[154:157], v[230:233], v[78:81]
	v_mfma_f32_16x16x32_bf16 v[74:77], v[162:165], v[230:233], v[74:77]
	v_mfma_f32_16x16x32_bf16 v[118:121], v[166:169], v[182:185], v[118:121]
	v_mfma_f32_16x16x32_bf16 v[114:117], v[174:177], v[182:185], v[114:117]
	v_mfma_f32_16x16x32_bf16 v[102:105], v[166:169], v[200:203], v[102:105]
	v_mfma_f32_16x16x32_bf16 v[98:101], v[174:177], v[200:203], v[98:101]
	v_mfma_f32_16x16x32_bf16 v[86:89], v[166:169], v[208:211], v[86:89]
	v_mfma_f32_16x16x32_bf16 v[82:85], v[174:177], v[208:211], v[82:85]
	v_mfma_f32_16x16x32_bf16 v[70:73], v[166:169], v[220:223], v[70:73]
	v_mfma_f32_16x16x32_bf16 v[66:69], v[174:177], v[220:223], v[66:69]
	v_mfma_f32_16x16x32_bf16 v[118:121], v[170:173], v[188:191], v[118:121]
	v_mfma_f32_16x16x32_bf16 v[114:117], v[178:181], v[188:191], v[114:117]
	v_mfma_f32_16x16x32_bf16 v[102:105], v[170:173], v[204:207], v[102:105]
	v_mfma_f32_16x16x32_bf16 v[98:101], v[178:181], v[204:207], v[98:101]
	v_mfma_f32_16x16x32_bf16 v[86:89], v[170:173], v[212:215], v[86:89]
	v_mfma_f32_16x16x32_bf16 v[82:85], v[178:181], v[212:215], v[82:85]
	v_mfma_f32_16x16x32_bf16 v[70:73], v[170:173], v[230:233], v[70:73]
	v_mfma_f32_16x16x32_bf16 v[66:69], v[178:181], v[230:233], v[66:69]
	s_barrier
	s_add_i32 s60, s62, s42
	v_lshl_add_u64 v[192:193], s[36:37], 0, v[194:195]
	s_mov_b32 m0, s60
	ds_read_b128 v[182:185], v149 offset:16384
	ds_read_b128 v[188:191], v149 offset:17408
	ds_read_b128 v[200:203], v149 offset:18432
	ds_read_b128 v[204:207], v149 offset:19456
	ds_read_b128 v[208:211], v149 offset:20480
	ds_read_b128 v[212:215], v149 offset:21504
	ds_read_b128 v[220:223], v149 offset:22528
	ds_read_b128 v[230:233], v149 offset:23552
	global_load_lds_dwordx4 v[192:193], off
	s_add_i32 m0, s60, 0x2000
	s_add_u32 s60, s36, 0x80000
	v_lshl_add_u64 v[234:235], s[36:37], 0, v[134:135]
	s_addc_u32 s61, s37, 0
	s_add_i32 s62, s63, s42
	global_load_lds_dwordx4 v[234:235], off
	v_lshl_add_u64 v[236:237], s[60:61], 0, v[194:195]
	s_mov_b32 m0, s62
	v_lshl_add_u64 v[238:239], s[38:39], 0, v[132:133]
	global_load_lds_dwordx4 v[236:237], off
	v_lshl_add_u64 v[236:237], s[60:61], 0, v[134:135]
	s_add_i32 m0, s62, 0x2000
	s_nop 0
	global_load_lds_dwordx4 v[236:237], off
	v_lshl_add_u64 v[236:237], s[38:39], 0, v[130:131]
	s_mov_b32 m0, s1
	s_nop 0
	global_load_lds_dwordx4 v[236:237], off
	s_mov_b32 m0, s43
	s_nop 0
	global_load_lds_dwordx4 v[238:239], off
	s_waitcnt vmcnt(8)
	s_waitcnt lgkmcnt(0)
	s_barrier
; #define PG8_STAGE(bufoff, gbase, voff) do { _Pragma("unroll") for (int _i = 0; _i < 2; ++_i) \
;         __builtin_amdgcn_global_load_lds((const unsigned*)((const char*)(gbase) + (voff)[_i]), (PG8_LAS unsigned*)(lds + (bufoff) + ldsw + _i * 8192), 16, 0, PG8_AUX_##voff); } while (0)
; #define PG8_LDA(dst, b, h) do { _Pragma("unroll") for (int m = 0; m < 4; ++m) _Pragma("unroll") for (int k = 0; k < 2; ++k) dst[m][k] = *(const PG8_LAS bf16x8*)(lds + PG8_SA(b, h) + aoff + m * 2048 + k * 1024); } while (0)
; #define PG8_LDB(dst, b, h) do { _Pragma("unroll") for (int n = 0; n < 2; ++n) _Pragma("unroll") for (int k = 0; k < 2; ++k) dst[n][k] = *(const PG8_LAS bf16x8*)(lds + PG8_SB(b, h) + boff + n * 2048 + k * 1024); } while (0)
; #define PG8_MMA(ai, bj, At, Bt) do { __builtin_amdgcn_s_setprio(1); _Pragma("unroll") for (int m = 0; m < 4; ++m) _Pragma("unroll") for (int n = 0; n < 2; ++n) _Pragma("unroll") for (int k = 0; k < 2; ++k) \
;         acc[ai][bj][m][n] = __builtin_amdgcn_mfma_f32_16x16x32_bf16(Bt[n][k], At[m][k], acc[ai][bj][m][n], 0, 0, 0); __builtin_amdgcn_s_setprio(0); } while (0)
; #define PG8_WAIT_V(n) asm volatile("s_waitcnt vmcnt(" #n ")" ::: "memory")
; #define PG8_WAIT_L(n) asm volatile("s_waitcnt lgkmcnt(" #n ")" ::: "memory")
; #define PG8_BAR __builtin_amdgcn_s_barrier()
; #define PG8_SCHED __builtin_amdgcn_sched_barrier(0)
;     ...
;             PG8_WAIT_V(8); PG8_WAIT_L(0); PG8_BAR; PG8_MMA(1, 0, At, B0); PG8_MMA(1, 1, At, B1); PG8_BAR; PG8_SCHED;
;             PG8_LDB(B0, 1, 0); PG8_LDB(B1, 1, 1); PG8_SCHED; PG8_LDA(At, 1, 0); PG8_STAGE(PG8_SA(0, 1), a2 + hstep, voffA);
;             PG8_WAIT_V(8); PG8_WAIT_L(0); PG8_BAR; PG8_MMA(0, 0, At, B0); PG8_MMA(0, 1, At, B1); PG8_BAR; PG8_SCHED;
	v_mfma_f32_16x16x32_bf16 v[62:65], v[150:153], v[182:185], v[62:65]
	v_mfma_f32_16x16x32_bf16 v[58:61], v[158:161], v[182:185], v[58:61]
	v_mfma_f32_16x16x32_bf16 v[46:49], v[150:153], v[200:203], v[46:49]
	v_mfma_f32_16x16x32_bf16 v[42:45], v[158:161], v[200:203], v[42:45]
	v_mfma_f32_16x16x32_bf16 v[30:33], v[150:153], v[208:211], v[30:33]
	v_mfma_f32_16x16x32_bf16 v[26:29], v[158:161], v[208:211], v[26:29]
	v_mfma_f32_16x16x32_bf16 v[14:17], v[150:153], v[220:223], v[14:17]
	v_mfma_f32_16x16x32_bf16 v[10:13], v[158:161], v[220:223], v[10:13]
	v_mfma_f32_16x16x32_bf16 v[62:65], v[154:157], v[188:191], v[62:65]
	v_mfma_f32_16x16x32_bf16 v[58:61], v[162:165], v[188:191], v[58:61]
	v_mfma_f32_16x16x32_bf16 v[46:49], v[154:157], v[204:207], v[46:49]
	v_mfma_f32_16x16x32_bf16 v[42:45], v[162:165], v[204:207], v[42:45]
	v_mfma_f32_16x16x32_bf16 v[30:33], v[154:157], v[212:215], v[30:33]
	v_mfma_f32_16x16x32_bf16 v[26:29], v[162:165], v[212:215], v[26:29]
	v_mfma_f32_16x16x32_bf16 v[14:17], v[154:157], v[230:233], v[14:17]
	v_mfma_f32_16x16x32_bf16 v[10:13], v[162:165], v[230:233], v[10:13]
	v_mfma_f32_16x16x32_bf16 v[54:57], v[166:169], v[182:185], v[54:57]
	v_mfma_f32_16x16x32_bf16 v[50:53], v[174:177], v[182:185], v[50:53]
	v_mfma_f32_16x16x32_bf16 v[38:41], v[166:169], v[200:203], v[38:41]
	v_mfma_f32_16x16x32_bf16 v[34:37], v[174:177], v[200:203], v[34:37]
	v_mfma_f32_16x16x32_bf16 v[22:25], v[166:169], v[208:211], v[22:25]
	v_mfma_f32_16x16x32_bf16 v[18:21], v[174:177], v[208:211], v[18:21]
	v_mfma_f32_16x16x32_bf16 v[6:9], v[166:169], v[220:223], v[6:9]
	v_mfma_f32_16x16x32_bf16 v[2:5], v[174:177], v[220:223], v[2:5]
	v_mfma_f32_16x16x32_bf16 v[54:57], v[170:173], v[188:191], v[54:57]
	v_mfma_f32_16x16x32_bf16 v[50:53], v[178:181], v[188:191], v[50:53]
	v_mfma_f32_16x16x32_bf16 v[38:41], v[170:173], v[204:207], v[38:41]
	v_mfma_f32_16x16x32_bf16 v[34:37], v[178:181], v[204:207], v[34:37]
	v_mfma_f32_16x16x32_bf16 v[22:25], v[170:173], v[212:215], v[22:25]
	v_mfma_f32_16x16x32_bf16 v[18:21], v[178:181], v[212:215], v[18:21]
	v_mfma_f32_16x16x32_bf16 v[6:9], v[170:173], v[230:233], v[6:9]
	v_mfma_f32_16x16x32_bf16 v[2:5], v[178:181], v[230:233], v[2:5]
	s_barrier
	s_add_i32 s60, 0, 0x18000
	s_add_i32 s61, 0, 0x1c000
	v_add_u32_e32 v162, s60, v146
	v_add_u32_e32 v178, s61, v146
	ds_read_b128 v[150:153], v162
	ds_read_b128 v[154:157], v162 offset:1024
	ds_read_b128 v[158:161], v162 offset:2048
	ds_read_b128 v[162:165], v162 offset:3072
	ds_read_b128 v[166:169], v178
	ds_read_b128 v[170:173], v178 offset:1024
	ds_read_b128 v[174:177], v178 offset:2048
	ds_read_b128 v[178:181], v178 offset:3072
	s_add_u32 s38, s38, 0x80000
	s_addc_u32 s39, s39, 0
	s_mov_b32 m0, s44
	v_lshl_add_u64 v[240:241], s[38:39], 0, v[130:131]
	ds_read_b128 v[182:185], v149 offset:32768
	ds_read_b128 v[188:191], v149 offset:33792
	ds_read_b128 v[200:203], v149 offset:34816
	ds_read_b128 v[204:207], v149 offset:35840
	ds_read_b128 v[208:211], v149 offset:36864
	ds_read_b128 v[212:215], v149 offset:37888
	ds_read_b128 v[220:223], v149 offset:38912
	ds_read_b128 v[230:233], v149 offset:39936
	global_load_lds_dwordx4 v[240:241], off
	v_lshl_add_u64 v[240:241], s[38:39], 0, v[132:133]
	s_mov_b32 m0, s45
	s_nop 0
	global_load_lds_dwordx4 v[240:241], off
	s_waitcnt vmcnt(8)
	s_waitcnt lgkmcnt(0)
	s_barrier
	v_mfma_f32_16x16x32_bf16 v[122:125], v[150:153], v[182:185], v[122:125]
	v_mfma_f32_16x16x32_bf16 v[126:129], v[158:161], v[182:185], v[126:129]
	v_mfma_f32_16x16x32_bf16 v[110:113], v[150:153], v[200:203], v[110:113]
	v_mfma_f32_16x16x32_bf16 v[106:109], v[158:161], v[200:203], v[106:109]
	v_mfma_f32_16x16x32_bf16 v[94:97], v[150:153], v[208:211], v[94:97]
	v_mfma_f32_16x16x32_bf16 v[90:93], v[158:161], v[208:211], v[90:93]
	v_mfma_f32_16x16x32_bf16 v[78:81], v[150:153], v[220:223], v[78:81]
	v_mfma_f32_16x16x32_bf16 v[74:77], v[158:161], v[220:223], v[74:77]
	v_mfma_f32_16x16x32_bf16 v[122:125], v[154:157], v[188:191], v[122:125]
	v_mfma_f32_16x16x32_bf16 v[126:129], v[162:165], v[188:191], v[126:129]
	v_mfma_f32_16x16x32_bf16 v[110:113], v[154:157], v[204:207], v[110:113]
	v_mfma_f32_16x16x32_bf16 v[106:109], v[162:165], v[204:207], v[106:109]
	v_mfma_f32_16x16x32_bf16 v[94:97], v[154:157], v[212:215], v[94:97]
	v_mfma_f32_16x16x32_bf16 v[90:93], v[162:165], v[212:215], v[90:93]
	v_mfma_f32_16x16x32_bf16 v[78:81], v[154:157], v[230:233], v[78:81]
	v_mfma_f32_16x16x32_bf16 v[74:77], v[162:165], v[230:233], v[74:77]
	v_mfma_f32_16x16x32_bf16 v[118:121], v[166:169], v[182:185], v[118:121]
	v_mfma_f32_16x16x32_bf16 v[114:117], v[174:177], v[182:185], v[114:117]
	v_mfma_f32_16x16x32_bf16 v[102:105], v[166:169], v[200:203], v[102:105]
	v_mfma_f32_16x16x32_bf16 v[98:101], v[174:177], v[200:203], v[98:101]
	v_mfma_f32_16x16x32_bf16 v[86:89], v[166:169], v[208:211], v[86:89]
	v_mfma_f32_16x16x32_bf16 v[82:85], v[174:177], v[208:211], v[82:85]
	v_mfma_f32_16x16x32_bf16 v[70:73], v[166:169], v[220:223], v[70:73]
	v_mfma_f32_16x16x32_bf16 v[66:69], v[174:177], v[220:223], v[66:69]
	v_mfma_f32_16x16x32_bf16 v[118:121], v[170:173], v[188:191], v[118:121]
	v_mfma_f32_16x16x32_bf16 v[114:117], v[178:181], v[188:191], v[114:117]
	v_mfma_f32_16x16x32_bf16 v[102:105], v[170:173], v[204:207], v[102:105]
	v_mfma_f32_16x16x32_bf16 v[98:101], v[178:181], v[204:207], v[98:101]
	v_mfma_f32_16x16x32_bf16 v[86:89], v[170:173], v[212:215], v[86:89]
	v_mfma_f32_16x16x32_bf16 v[82:85], v[178:181], v[212:215], v[82:85]
	v_mfma_f32_16x16x32_bf16 v[70:73], v[170:173], v[230:233], v[70:73]
	v_mfma_f32_16x16x32_bf16 v[66:69], v[178:181], v[230:233], v[66:69]
	s_barrier
; #define PG8_STAGE(bufoff, gbase, voff) do { _Pragma("unroll") for (int _i = 0; _i < 2; ++_i) \
;         __builtin_amdgcn_global_load_lds((const unsigned*)((const char*)(gbase) + (voff)[_i]), (PG8_LAS unsigned*)(lds + (bufoff) + ldsw + _i * 8192), 16, 0, PG8_AUX_##voff); } while (0)
; #define PG8_LDA(dst, b, h) do { _Pragma("unroll") for (int m = 0; m < 4; ++m) _Pragma("unroll") for (int k = 0; k < 2; ++k) dst[m][k] = *(const PG8_LAS bf16x8*)(lds + PG8_SA(b, h) + aoff + m * 2048 + k * 1024); } while (0)
; #define PG8_LDB(dst, b, h) do { _Pragma("unroll") for (int n = 0; n < 2; ++n) _Pragma("unroll") for (int k = 0; k < 2; ++k) dst[n][k] = *(const PG8_LAS bf16x8*)(lds + PG8_SB(b, h) + boff + n * 2048 + k * 1024); } while (0)
; #define PG8_WAIT_V(n) asm volatile("s_waitcnt vmcnt(" #n ")" ::: "memory")
; #define PG8_BAR __builtin_amdgcn_s_barrier()
;     ...
;         for (int t = 0; t < nt; t += 2) {
;             const bool last = (t == nt - 2);
;             const char* a1 = cA + (size_t)(t + 1) * kstep;
;             const char* a2 = last ? nA : cA + (size_t)(t + 2) * kstep; const char* b2 = last ? nB : cB + (size_t)(t + 2) * kstep;
;             const char* a3 = a2 + kstep; const char* b3 = b2 + kstep;
;             if (last && has_next) S.a_ready(nxt);
;             if constexpr (SP2) {
;             PG8_LDB(B0, 0, 0); PG8_LDB(B1, 0, 1); PG8_SCHED; PG8_LDA(At, 0, 0); PG8_STAGE(PG8_SA(1, 1), a1 + hstep, voffA);
;             PG8_WAIT_V(8); PG8_WAIT_L(0); PG8_BAR; PG8_MMA(0, 0, At, B0); PG8_MMA(0, 1, At, B1); PG8_BAR; PG8_SCHED;
;             PG8_LDA(At, 0, 1); PG8_STAGE(PG8_SB(0, 0), b2, voffB); PG8_STAGE(PG8_SB(0, 1), b2 + hstep, voffB); PG8_STAGE(PG8_SA(0, 0), a2, voffA);
;             PG8_WAIT_V(8); PG8_WAIT_L(0); PG8_BAR; PG8_MMA(1, 0, At, B0); PG8_MMA(1, 1, At, B1); PG8_BAR; PG8_SCHED;
;             PG8_LDB(B0, 1, 0); PG8_LDB(B1, 1, 1); PG8_SCHED; PG8_LDA(At, 1, 0); PG8_STAGE(PG8_SA(0, 1), a2 + hstep, voffA);
;             PG8_WAIT_V(8); PG8_WAIT_L(0); PG8_BAR; PG8_MMA(0, 0, At, B0); PG8_MMA(0, 1, At, B1); PG8_BAR; PG8_SCHED;
;             PG8_LDA(At, 1, 1); PG8_STAGE(PG8_SB(1, 0), b3, voffB); PG8_STAGE(PG8_SB(1, 1), b3 + hstep, voffB); PG8_STAGE(PG8_SA(1, 0), a3, voffA);
;             PG8_WAIT_V(8); PG8_WAIT_L(0); PG8_BAR; PG8_MMA(1, 0, At, B0); PG8_MMA(1, 1, At, B1); PG8_BAR; PG8_SCHED;
;     ...
;         if constexpr (ALIGN_EPI) { if (wr == 0) PG8_BAR; }
	s_add_i32 s38, s60, s42
	v_lshl_add_u64 v[192:193], v[192:193], 0, s[2:3]
	s_mov_b32 m0, s38
	ds_read_b128 v[182:185], v149 offset:49152
	ds_read_b128 v[188:191], v149 offset:50176
	ds_read_b128 v[200:203], v149 offset:51200
	ds_read_b128 v[204:207], v149 offset:52224
	ds_read_b128 v[208:211], v149 offset:53248
	ds_read_b128 v[212:215], v149 offset:54272
	ds_read_b128 v[220:223], v149 offset:55296
	ds_read_b128 v[230:233], v149 offset:56320
	global_load_lds_dwordx4 v[192:193], off
	s_add_i32 m0, s38, 0x2000
	s_add_u32 s36, s36, 0x80080
	v_lshl_add_u64 v[192:193], v[234:235], 0, s[2:3]
	s_addc_u32 s37, s37, 0
	s_add_i32 s38, s61, s42
	global_load_lds_dwordx4 v[192:193], off
	v_lshl_add_u64 v[192:193], s[36:37], 0, v[194:195]
	s_mov_b32 m0, s38
	s_nop 0
	global_load_lds_dwordx4 v[192:193], off
	v_lshl_add_u64 v[192:193], s[36:37], 0, v[134:135]
	s_add_i32 m0, s38, 0x2000
	s_nop 0
	global_load_lds_dwordx4 v[192:193], off
	v_lshl_add_u64 v[192:193], v[236:237], 0, s[2:3]
	s_mov_b32 m0, s51
	s_nop 0
	global_load_lds_dwordx4 v[192:193], off
	v_lshl_add_u64 v[192:193], v[238:239], 0, s[2:3]
	s_mov_b32 m0, s52
	s_nop 0
	global_load_lds_dwordx4 v[192:193], off
	s_waitcnt vmcnt(8)
	s_waitcnt lgkmcnt(0)
	s_barrier
	v_mfma_f32_16x16x32_bf16 v[62:65], v[150:153], v[182:185], v[62:65]
	v_mfma_f32_16x16x32_bf16 v[58:61], v[158:161], v[182:185], v[58:61]
	v_mfma_f32_16x16x32_bf16 v[46:49], v[150:153], v[200:203], v[46:49]
	v_mfma_f32_16x16x32_bf16 v[42:45], v[158:161], v[200:203], v[42:45]
	v_mfma_f32_16x16x32_bf16 v[30:33], v[150:153], v[208:211], v[30:33]
	v_mfma_f32_16x16x32_bf16 v[26:29], v[158:161], v[208:211], v[26:29]
	v_mfma_f32_16x16x32_bf16 v[14:17], v[150:153], v[220:223], v[14:17]
	v_mfma_f32_16x16x32_bf16 v[10:13], v[158:161], v[220:223], v[10:13]
	v_mfma_f32_16x16x32_bf16 v[62:65], v[154:157], v[188:191], v[62:65]
	v_mfma_f32_16x16x32_bf16 v[58:61], v[162:165], v[188:191], v[58:61]
	v_mfma_f32_16x16x32_bf16 v[46:49], v[154:157], v[204:207], v[46:49]
	v_mfma_f32_16x16x32_bf16 v[42:45], v[162:165], v[204:207], v[42:45]
	v_mfma_f32_16x16x32_bf16 v[30:33], v[154:157], v[212:215], v[30:33]
	v_mfma_f32_16x16x32_bf16 v[26:29], v[162:165], v[212:215], v[26:29]
	v_mfma_f32_16x16x32_bf16 v[14:17], v[154:157], v[230:233], v[14:17]
	v_mfma_f32_16x16x32_bf16 v[10:13], v[162:165], v[230:233], v[10:13]
	v_mfma_f32_16x16x32_bf16 v[54:57], v[166:169], v[182:185], v[54:57]
	v_mfma_f32_16x16x32_bf16 v[50:53], v[174:177], v[182:185], v[50:53]
	v_mfma_f32_16x16x32_bf16 v[38:41], v[166:169], v[200:203], v[38:41]
	v_mfma_f32_16x16x32_bf16 v[34:37], v[174:177], v[200:203], v[34:37]
	v_mfma_f32_16x16x32_bf16 v[22:25], v[166:169], v[208:211], v[22:25]
	v_mfma_f32_16x16x32_bf16 v[18:21], v[174:177], v[208:211], v[18:21]
	v_mfma_f32_16x16x32_bf16 v[6:9], v[166:169], v[220:223], v[6:9]
	v_mfma_f32_16x16x32_bf16 v[2:5], v[174:177], v[220:223], v[2:5]
	v_mfma_f32_16x16x32_bf16 v[54:57], v[170:173], v[188:191], v[54:57]
	v_mfma_f32_16x16x32_bf16 v[50:53], v[178:181], v[188:191], v[50:53]
	v_mfma_f32_16x16x32_bf16 v[38:41], v[170:173], v[204:207], v[38:41]
	v_mfma_f32_16x16x32_bf16 v[34:37], v[178:181], v[204:207], v[34:37]
	v_mfma_f32_16x16x32_bf16 v[22:25], v[170:173], v[212:215], v[22:25]
	v_mfma_f32_16x16x32_bf16 v[18:21], v[178:181], v[212:215], v[18:21]
	v_mfma_f32_16x16x32_bf16 v[6:9], v[170:173], v[230:233], v[6:9]
	v_mfma_f32_16x16x32_bf16 v[2:5], v[178:181], v[230:233], v[2:5]
	s_barrier
	s_add_i32 s36, s59, 2
	s_add_u32 s34, s34, 0x100
	s_addc_u32 s35, s35, 0
	v_lshl_add_u64 v[142:143], v[142:143], 0, vcc
	v_lshl_add_u64 v[140:141], v[140:141], 0, vcc
	s_cmp_ge_i32 s59, s13
	s_mov_b32 s59, s36
	s_cbranch_scc0 .LBB0_1797
	s_and_b64 vcc, exec, s[10:11]
	s_cbranch_vccz .LBB0_1800
	s_barrier

; #define PG8_STAGE(bufoff, gbase, voff) do { _Pragma("unroll") for (int _i = 0; _i < 2; ++_i) \
;         __builtin_amdgcn_global_load_lds((const unsigned*)((const char*)(gbase) + (voff)[_i]), (PG8_LAS unsigned*)(lds + (bufoff) + ldsw + _i * 8192), 16, 0, PG8_AUX_##voff); } while (0)
; #define PG8_LDA(dst, b, h) do { _Pragma("unroll") for (int m = 0; m < 4; ++m) _Pragma("unroll") for (int k = 0; k < 2; ++k) dst[m][k] = *(const PG8_LAS bf16x8*)(lds + PG8_SA(b, h) + aoff + m * 2048 + k * 1024); } while (0)
; #define PG8_LDB(dst, b, h) do { _Pragma("unroll") for (int n = 0; n < 2; ++n) _Pragma("unroll") for (int k = 0; k < 2; ++k) dst[n][k] = *(const PG8_LAS bf16x8*)(lds + PG8_SB(b, h) + boff + n * 2048 + k * 1024); } while (0)
; #define PG8_MMA(ai, bj, At, Bt) do { __builtin_amdgcn_s_setprio(1); _Pragma("unroll") for (int m = 0; m < 4; ++m) _Pragma("unroll") for (int n = 0; n < 2; ++n) _Pragma("unroll") for (int k = 0; k < 2; ++k) \
;         acc[ai][bj][m][n] = __builtin_amdgcn_mfma_f32_16x16x32_bf16(Bt[n][k], At[m][k], acc[ai][bj][m][n], 0, 0, 0); __builtin_amdgcn_s_setprio(0); } while (0)
; #define PG8_WAIT_V(n) asm volatile("s_waitcnt vmcnt(" #n ")" ::: "memory")
; #define PG8_WAIT_L(n) asm volatile("s_waitcnt lgkmcnt(" #n ")" ::: "memory")
; #define PG8_BAR __builtin_amdgcn_s_barrier()
; #define PG8_SCHED __builtin_amdgcn_sched_barrier(0)
;     ...
;         for (int t = 0; t < nt; t += 2) {
;             const bool last = (t == nt - 2);
;             const char* a1 = cA + (size_t)(t + 1) * kstep;
;             const char* a2 = last ? nA : cA + (size_t)(t + 2) * kstep; const char* b2 = last ? nB : cB + (size_t)(t + 2) * kstep;
;             const char* a3 = a2 + kstep; const char* b3 = b2 + kstep;
;             if (last && has_next) S.a_ready(nxt);
;             if constexpr (SP2) {
;             PG8_LDB(B0, 0, 0); PG8_LDB(B1, 0, 1); PG8_SCHED; PG8_LDA(At, 0, 0); PG8_STAGE(PG8_SA(1, 1), a1 + hstep, voffA);
;             PG8_WAIT_V(8); PG8_WAIT_L(0); PG8_BAR; PG8_MMA(0, 0, At, B0); PG8_MMA(0, 1, At, B1); PG8_BAR; PG8_SCHED;
;             PG8_LDA(At, 0, 1); PG8_STAGE(PG8_SB(0, 0), b2, voffB); PG8_STAGE(PG8_SB(0, 1), b2 + hstep, voffB); PG8_STAGE(PG8_SA(0, 0), a2, voffA);
;             PG8_WAIT_V(8); PG8_WAIT_L(0); PG8_BAR; PG8_MMA(1, 0, At, B0); PG8_MMA(1, 1, At, B1); PG8_BAR; PG8_SCHED;
.LBB0_2328:
	s_add_u32 s34, s28, s30
	s_addc_u32 s35, s29, s31
	s_add_u32 s59, s26, s30
	s_addc_u32 s60, s27, s31
	s_add_i32 s61, 0, 0x10000
	s_cmp_eq_u32 s21, s23
	s_cselect_b32 s37, s5, s35
	s_cselect_b32 s36, s4, s34
	v_add_u32_e32 v151, s61, v146
	s_cselect_b32 s35, s25, s60
	s_cselect_b32 s34, s24, s59
	s_add_i32 s59, 0, 0x14000
	ds_read_b128 v[152:155], v151
	ds_read_b128 v[156:159], v151 offset:1024
	ds_read_b128 v[160:163], v151 offset:2048
	ds_read_b128 v[164:167], v151 offset:3072
	v_add_u32_e32 v151, s59, v146
	ds_read_b128 v[168:171], v151
	ds_read_b128 v[172:175], v151 offset:1024
	ds_read_b128 v[176:179], v151 offset:2048
	ds_read_b128 v[180:183], v151 offset:3072
	v_lshl_add_u64 v[234:235], s[28:29], 0, v[142:143]
	s_add_i32 m0, s42, 0xc000
	ds_read_b128 v[186:189], v150
	ds_read_b128 v[190:193], v150 offset:1024
	ds_read_b128 v[200:203], v150 offset:2048
	ds_read_b128 v[204:207], v150 offset:3072
	ds_read_b128 v[208:211], v150 offset:4096
	ds_read_b128 v[212:215], v150 offset:5120
	ds_read_b128 v[220:223], v150 offset:6144
	ds_read_b128 v[230:233], v150 offset:7168
	global_load_lds_dwordx4 v[234:235], off
	v_lshl_add_u64 v[234:235], s[28:29], 0, v[140:141]
	s_add_i32 m0, s42, 0xe000
	s_nop 0
	global_load_lds_dwordx4 v[234:235], off
	s_waitcnt vmcnt(8)
	s_waitcnt lgkmcnt(0)
	s_barrier
	v_mfma_f32_16x16x32_bf16 v[126:129], v[152:155], v[186:189], v[126:129]
	v_mfma_f32_16x16x32_bf16 v[122:125], v[160:163], v[186:189], v[122:125]
	v_mfma_f32_16x16x32_bf16 v[110:113], v[152:155], v[200:203], v[110:113]
	v_mfma_f32_16x16x32_bf16 v[106:109], v[160:163], v[200:203], v[106:109]
	v_mfma_f32_16x16x32_bf16 v[94:97], v[152:155], v[208:211], v[94:97]
	v_mfma_f32_16x16x32_bf16 v[90:93], v[160:163], v[208:211], v[90:93]
	v_mfma_f32_16x16x32_bf16 v[78:81], v[152:155], v[220:223], v[78:81]
	v_mfma_f32_16x16x32_bf16 v[74:77], v[160:163], v[220:223], v[74:77]
	v_mfma_f32_16x16x32_bf16 v[126:129], v[156:159], v[190:193], v[126:129]
	v_mfma_f32_16x16x32_bf16 v[122:125], v[164:167], v[190:193], v[122:125]
	v_mfma_f32_16x16x32_bf16 v[110:113], v[156:159], v[204:207], v[110:113]
	v_mfma_f32_16x16x32_bf16 v[106:109], v[164:167], v[204:207], v[106:109]
	v_mfma_f32_16x16x32_bf16 v[94:97], v[156:159], v[212:215], v[94:97]
	v_mfma_f32_16x16x32_bf16 v[90:93], v[164:167], v[212:215], v[90:93]
	v_mfma_f32_16x16x32_bf16 v[78:81], v[156:159], v[230:233], v[78:81]
	v_mfma_f32_16x16x32_bf16 v[74:77], v[164:167], v[230:233], v[74:77]
	v_mfma_f32_16x16x32_bf16 v[118:121], v[168:171], v[186:189], v[118:121]
	v_mfma_f32_16x16x32_bf16 v[114:117], v[176:179], v[186:189], v[114:117]
	v_mfma_f32_16x16x32_bf16 v[102:105], v[168:171], v[200:203], v[102:105]
	v_mfma_f32_16x16x32_bf16 v[98:101], v[176:179], v[200:203], v[98:101]
	v_mfma_f32_16x16x32_bf16 v[86:89], v[168:171], v[208:211], v[86:89]
	v_mfma_f32_16x16x32_bf16 v[82:85], v[176:179], v[208:211], v[82:85]
	v_mfma_f32_16x16x32_bf16 v[70:73], v[168:171], v[220:223], v[70:73]
	v_mfma_f32_16x16x32_bf16 v[66:69], v[176:179], v[220:223], v[66:69]
	v_mfma_f32_16x16x32_bf16 v[118:121], v[172:175], v[190:193], v[118:121]
	v_mfma_f32_16x16x32_bf16 v[114:117], v[180:183], v[190:193], v[114:117]
	v_mfma_f32_16x16x32_bf16 v[102:105], v[172:175], v[204:207], v[102:105]
	v_mfma_f32_16x16x32_bf16 v[98:101], v[180:183], v[204:207], v[98:101]
	v_mfma_f32_16x16x32_bf16 v[86:89], v[172:175], v[212:215], v[86:89]
	v_mfma_f32_16x16x32_bf16 v[82:85], v[180:183], v[212:215], v[82:85]
	v_mfma_f32_16x16x32_bf16 v[70:73], v[172:175], v[230:233], v[70:73]
	v_mfma_f32_16x16x32_bf16 v[66:69], v[180:183], v[230:233], v[66:69]
	s_barrier
	s_add_i32 s60, s61, s41
	v_lshl_add_u64 v[234:235], s[34:35], 0, v[194:195]
	s_mov_b32 m0, s60
	ds_read_b128 v[186:189], v150 offset:16384
	ds_read_b128 v[190:193], v150 offset:17408
	ds_read_b128 v[200:203], v150 offset:18432
	ds_read_b128 v[204:207], v150 offset:19456
	ds_read_b128 v[208:211], v150 offset:20480
	ds_read_b128 v[212:215], v150 offset:21504
	ds_read_b128 v[220:223], v150 offset:22528
	ds_read_b128 v[230:233], v150 offset:23552
	global_load_lds_dwordx4 v[234:235], off
	s_add_i32 m0, s60, 0x2000
	s_add_u32 s60, s34, 0x160000
	v_lshl_add_u64 v[236:237], s[34:35], 0, v[134:135]
	s_addc_u32 s61, s35, 0
	s_add_i32 s59, s59, s41
	global_load_lds_dwordx4 v[236:237], off
	v_lshl_add_u64 v[238:239], s[60:61], 0, v[194:195]
	s_mov_b32 m0, s59
	v_lshl_add_u64 v[240:241], s[36:37], 0, v[132:133]
	global_load_lds_dwordx4 v[238:239], off
	v_lshl_add_u64 v[238:239], s[60:61], 0, v[134:135]
	s_add_i32 m0, s59, 0x2000
	s_nop 0
	global_load_lds_dwordx4 v[238:239], off
	v_lshl_add_u64 v[238:239], s[36:37], 0, v[130:131]
	s_mov_b32 m0, s42
	s_nop 0
	global_load_lds_dwordx4 v[238:239], off
	s_mov_b32 m0, s44
	s_nop 0
	global_load_lds_dwordx4 v[240:241], off
	s_waitcnt vmcnt(8)
	s_waitcnt lgkmcnt(0)
	s_barrier
; #define PG8_STAGE(bufoff, gbase, voff) do { _Pragma("unroll") for (int _i = 0; _i < 2; ++_i) \
;         __builtin_amdgcn_global_load_lds((const unsigned*)((const char*)(gbase) + (voff)[_i]), (PG8_LAS unsigned*)(lds + (bufoff) + ldsw + _i * 8192), 16, 0, PG8_AUX_##voff); } while (0)
; #define PG8_LDA(dst, b, h) do { _Pragma("unroll") for (int m = 0; m < 4; ++m) _Pragma("unroll") for (int k = 0; k < 2; ++k) dst[m][k] = *(const PG8_LAS bf16x8*)(lds + PG8_SA(b, h) + aoff + m * 2048 + k * 1024); } while (0)
; #define PG8_LDB(dst, b, h) do { _Pragma("unroll") for (int n = 0; n < 2; ++n) _Pragma("unroll") for (int k = 0; k < 2; ++k) dst[n][k] = *(const PG8_LAS bf16x8*)(lds + PG8_SB(b, h) + boff + n * 2048 + k * 1024); } while (0)
; #define PG8_MMA(ai, bj, At, Bt) do { __builtin_amdgcn_s_setprio(1); _Pragma("unroll") for (int m = 0; m < 4; ++m) _Pragma("unroll") for (int n = 0; n < 2; ++n) _Pragma("unroll") for (int k = 0; k < 2; ++k) \
;         acc[ai][bj][m][n] = __builtin_amdgcn_mfma_f32_16x16x32_bf16(Bt[n][k], At[m][k], acc[ai][bj][m][n], 0, 0, 0); __builtin_amdgcn_s_setprio(0); } while (0)
; #define PG8_WAIT_V(n) asm volatile("s_waitcnt vmcnt(" #n ")" ::: "memory")
; #define PG8_WAIT_L(n) asm volatile("s_waitcnt lgkmcnt(" #n ")" ::: "memory")
; #define PG8_BAR __builtin_amdgcn_s_barrier()
; #define PG8_SCHED __builtin_amdgcn_sched_barrier(0)
;     ...
;             PG8_WAIT_V(8); PG8_WAIT_L(0); PG8_BAR; PG8_MMA(1, 0, At, B0); PG8_MMA(1, 1, At, B1); PG8_BAR; PG8_SCHED;
;             PG8_LDB(B0, 1, 0); PG8_LDB(B1, 1, 1); PG8_SCHED; PG8_LDA(At, 1, 0); PG8_STAGE(PG8_SA(0, 1), a2 + hstep, voffA);
;             PG8_WAIT_V(8); PG8_WAIT_L(0); PG8_BAR; PG8_MMA(0, 0, At, B0); PG8_MMA(0, 1, At, B1); PG8_BAR; PG8_SCHED;
	v_mfma_f32_16x16x32_bf16 v[62:65], v[152:155], v[186:189], v[62:65]
	v_mfma_f32_16x16x32_bf16 v[58:61], v[160:163], v[186:189], v[58:61]
	v_mfma_f32_16x16x32_bf16 v[46:49], v[152:155], v[200:203], v[46:49]
	v_mfma_f32_16x16x32_bf16 v[42:45], v[160:163], v[200:203], v[42:45]
	v_mfma_f32_16x16x32_bf16 v[30:33], v[152:155], v[208:211], v[30:33]
	v_mfma_f32_16x16x32_bf16 v[26:29], v[160:163], v[208:211], v[26:29]
	v_mfma_f32_16x16x32_bf16 v[14:17], v[152:155], v[220:223], v[14:17]
	v_mfma_f32_16x16x32_bf16 v[10:13], v[160:163], v[220:223], v[10:13]
	v_mfma_f32_16x16x32_bf16 v[62:65], v[156:159], v[190:193], v[62:65]
	v_mfma_f32_16x16x32_bf16 v[58:61], v[164:167], v[190:193], v[58:61]
	v_mfma_f32_16x16x32_bf16 v[46:49], v[156:159], v[204:207], v[46:49]
	v_mfma_f32_16x16x32_bf16 v[42:45], v[164:167], v[204:207], v[42:45]
	v_mfma_f32_16x16x32_bf16 v[30:33], v[156:159], v[212:215], v[30:33]
	v_mfma_f32_16x16x32_bf16 v[26:29], v[164:167], v[212:215], v[26:29]
	v_mfma_f32_16x16x32_bf16 v[14:17], v[156:159], v[230:233], v[14:17]
	v_mfma_f32_16x16x32_bf16 v[10:13], v[164:167], v[230:233], v[10:13]
	v_mfma_f32_16x16x32_bf16 v[54:57], v[168:171], v[186:189], v[54:57]
	v_mfma_f32_16x16x32_bf16 v[50:53], v[176:179], v[186:189], v[50:53]
	v_mfma_f32_16x16x32_bf16 v[38:41], v[168:171], v[200:203], v[38:41]
	v_mfma_f32_16x16x32_bf16 v[34:37], v[176:179], v[200:203], v[34:37]
	v_mfma_f32_16x16x32_bf16 v[22:25], v[168:171], v[208:211], v[22:25]
	v_mfma_f32_16x16x32_bf16 v[18:21], v[176:179], v[208:211], v[18:21]
	v_mfma_f32_16x16x32_bf16 v[6:9], v[168:171], v[220:223], v[6:9]
	v_mfma_f32_16x16x32_bf16 v[2:5], v[176:179], v[220:223], v[2:5]
	v_mfma_f32_16x16x32_bf16 v[54:57], v[172:175], v[190:193], v[54:57]
	v_mfma_f32_16x16x32_bf16 v[50:53], v[180:183], v[190:193], v[50:53]
	v_mfma_f32_16x16x32_bf16 v[38:41], v[172:175], v[204:207], v[38:41]
	v_mfma_f32_16x16x32_bf16 v[34:37], v[180:183], v[204:207], v[34:37]
	v_mfma_f32_16x16x32_bf16 v[22:25], v[172:175], v[212:215], v[22:25]
	v_mfma_f32_16x16x32_bf16 v[18:21], v[180:183], v[212:215], v[18:21]
	v_mfma_f32_16x16x32_bf16 v[6:9], v[172:175], v[230:233], v[6:9]
	v_mfma_f32_16x16x32_bf16 v[2:5], v[180:183], v[230:233], v[2:5]
	s_barrier
	s_add_i32 s59, 0, 0x18000
	v_add_u32_e32 v151, s59, v146
	s_add_i32 s60, 0, 0x1c000
	ds_read_b128 v[152:155], v151
	ds_read_b128 v[156:159], v151 offset:1024
	ds_read_b128 v[160:163], v151 offset:2048
	ds_read_b128 v[164:167], v151 offset:3072
	v_add_u32_e32 v151, s60, v146
	ds_read_b128 v[168:171], v151
	ds_read_b128 v[172:175], v151 offset:1024
	ds_read_b128 v[176:179], v151 offset:2048
	ds_read_b128 v[180:183], v151 offset:3072
	s_add_u32 s36, s36, 0x160000
	s_addc_u32 s37, s37, 0
	s_mov_b32 m0, s45
	v_lshl_add_u64 v[242:243], s[36:37], 0, v[130:131]
	ds_read_b128 v[186:189], v150 offset:32768
	ds_read_b128 v[190:193], v150 offset:33792
	ds_read_b128 v[200:203], v150 offset:34816
	ds_read_b128 v[204:207], v150 offset:35840
	ds_read_b128 v[208:211], v150 offset:36864
	ds_read_b128 v[212:215], v150 offset:37888
	ds_read_b128 v[220:223], v150 offset:38912
	ds_read_b128 v[230:233], v150 offset:39936
	global_load_lds_dwordx4 v[242:243], off
	v_lshl_add_u64 v[242:243], s[36:37], 0, v[132:133]
	s_mov_b32 m0, s46
	s_nop 0
	global_load_lds_dwordx4 v[242:243], off
	s_waitcnt vmcnt(8)
	s_waitcnt lgkmcnt(0)
	s_barrier
	v_mfma_f32_16x16x32_bf16 v[126:129], v[152:155], v[186:189], v[126:129]
	v_mfma_f32_16x16x32_bf16 v[122:125], v[160:163], v[186:189], v[122:125]
	v_mfma_f32_16x16x32_bf16 v[110:113], v[152:155], v[200:203], v[110:113]
	v_mfma_f32_16x16x32_bf16 v[106:109], v[160:163], v[200:203], v[106:109]
	v_mfma_f32_16x16x32_bf16 v[94:97], v[152:155], v[208:211], v[94:97]
	v_mfma_f32_16x16x32_bf16 v[90:93], v[160:163], v[208:211], v[90:93]
	v_mfma_f32_16x16x32_bf16 v[78:81], v[152:155], v[220:223], v[78:81]
	v_mfma_f32_16x16x32_bf16 v[74:77], v[160:163], v[220:223], v[74:77]
	v_mfma_f32_16x16x32_bf16 v[126:129], v[156:159], v[190:193], v[126:129]
	v_mfma_f32_16x16x32_bf16 v[122:125], v[164:167], v[190:193], v[122:125]
	v_mfma_f32_16x16x32_bf16 v[110:113], v[156:159], v[204:207], v[110:113]
	v_mfma_f32_16x16x32_bf16 v[106:109], v[164:167], v[204:207], v[106:109]
	v_mfma_f32_16x16x32_bf16 v[94:97], v[156:159], v[212:215], v[94:97]
	v_mfma_f32_16x16x32_bf16 v[90:93], v[164:167], v[212:215], v[90:93]
	v_mfma_f32_16x16x32_bf16 v[78:81], v[156:159], v[230:233], v[78:81]
	v_mfma_f32_16x16x32_bf16 v[74:77], v[164:167], v[230:233], v[74:77]
	v_mfma_f32_16x16x32_bf16 v[118:121], v[168:171], v[186:189], v[118:121]
	v_mfma_f32_16x16x32_bf16 v[114:117], v[176:179], v[186:189], v[114:117]
	v_mfma_f32_16x16x32_bf16 v[102:105], v[168:171], v[200:203], v[102:105]
	v_mfma_f32_16x16x32_bf16 v[98:101], v[176:179], v[200:203], v[98:101]
	v_mfma_f32_16x16x32_bf16 v[86:89], v[168:171], v[208:211], v[86:89]
	v_mfma_f32_16x16x32_bf16 v[82:85], v[176:179], v[208:211], v[82:85]
	v_mfma_f32_16x16x32_bf16 v[70:73], v[168:171], v[220:223], v[70:73]
	v_mfma_f32_16x16x32_bf16 v[66:69], v[176:179], v[220:223], v[66:69]
	v_mfma_f32_16x16x32_bf16 v[118:121], v[172:175], v[190:193], v[118:121]
	v_mfma_f32_16x16x32_bf16 v[114:117], v[180:183], v[190:193], v[114:117]
	v_mfma_f32_16x16x32_bf16 v[102:105], v[172:175], v[204:207], v[102:105]
	v_mfma_f32_16x16x32_bf16 v[98:101], v[180:183], v[204:207], v[98:101]
	v_mfma_f32_16x16x32_bf16 v[86:89], v[172:175], v[212:215], v[86:89]
	v_mfma_f32_16x16x32_bf16 v[82:85], v[180:183], v[212:215], v[82:85]
	v_mfma_f32_16x16x32_bf16 v[70:73], v[172:175], v[230:233], v[70:73]
	v_mfma_f32_16x16x32_bf16 v[66:69], v[180:183], v[230:233], v[66:69]
	s_barrier
; #define PG8_STAGE(bufoff, gbase, voff) do { _Pragma("unroll") for (int _i = 0; _i < 2; ++_i) \
;         __builtin_amdgcn_global_load_lds((const unsigned*)((const char*)(gbase) + (voff)[_i]), (PG8_LAS unsigned*)(lds + (bufoff) + ldsw + _i * 8192), 16, 0, PG8_AUX_##voff); } while (0)
; #define PG8_LDA(dst, b, h) do { _Pragma("unroll") for (int m = 0; m < 4; ++m) _Pragma("unroll") for (int k = 0; k < 2; ++k) dst[m][k] = *(const PG8_LAS bf16x8*)(lds + PG8_SA(b, h) + aoff + m * 2048 + k * 1024); } while (0)
; #define PG8_LDB(dst, b, h) do { _Pragma("unroll") for (int n = 0; n < 2; ++n) _Pragma("unroll") for (int k = 0; k < 2; ++k) dst[n][k] = *(const PG8_LAS bf16x8*)(lds + PG8_SB(b, h) + boff + n * 2048 + k * 1024); } while (0)
; #define PG8_WAIT_V(n) asm volatile("s_waitcnt vmcnt(" #n ")" ::: "memory")
; #define PG8_WAIT_L(n) asm volatile("s_waitcnt lgkmcnt(" #n ")" ::: "memory")
;     ...
;         for (int t = 0; t < nt; t += 2) {
;             const bool last = (t == nt - 2);
;             const char* a1 = cA + (size_t)(t + 1) * kstep;
;             const char* a2 = last ? nA : cA + (size_t)(t + 2) * kstep; const char* b2 = last ? nB : cB + (size_t)(t + 2) * kstep;
;             const char* a3 = a2 + kstep; const char* b3 = b2 + kstep;
;             if (last && has_next) S.a_ready(nxt);
;             if constexpr (SP2) {
;             PG8_LDB(B0, 0, 0); PG8_LDB(B1, 0, 1); PG8_SCHED; PG8_LDA(At, 0, 0); PG8_STAGE(PG8_SA(1, 1), a1 + hstep, voffA);
;             PG8_WAIT_V(8); PG8_WAIT_L(0); PG8_BAR; PG8_MMA(0, 0, At, B0); PG8_MMA(0, 1, At, B1); PG8_BAR; PG8_SCHED;
;             PG8_LDA(At, 0, 1); PG8_STAGE(PG8_SB(0, 0), b2, voffB); PG8_STAGE(PG8_SB(0, 1), b2 + hstep, voffB); PG8_STAGE(PG8_SA(0, 0), a2, voffA);
;             PG8_WAIT_V(8); PG8_WAIT_L(0); PG8_BAR; PG8_MMA(1, 0, At, B0); PG8_MMA(1, 1, At, B1); PG8_BAR; PG8_SCHED;
;             PG8_LDB(B0, 1, 0); PG8_LDB(B1, 1, 1); PG8_SCHED; PG8_LDA(At, 1, 0); PG8_STAGE(PG8_SA(0, 1), a2 + hstep, voffA);
;             PG8_WAIT_V(8); PG8_WAIT_L(0); PG8_BAR; PG8_MMA(0, 0, At, B0); PG8_MMA(0, 1, At, B1); PG8_BAR; PG8_SCHED;
;             PG8_LDA(At, 1, 1); PG8_STAGE(PG8_SB(1, 0), b3, voffB); PG8_STAGE(PG8_SB(1, 1), b3 + hstep, voffB); PG8_STAGE(PG8_SA(1, 0), a3, voffA);
;             PG8_WAIT_V(8); PG8_WAIT_L(0); PG8_BAR; PG8_MMA(1, 0, At, B0); PG8_MMA(1, 1, At, B1); PG8_BAR; PG8_SCHED;
	s_add_i32 s36, s59, s41
	v_lshl_add_u64 v[234:235], v[234:235], 0, s[2:3]
	s_mov_b32 m0, s36
	ds_read_b128 v[186:189], v150 offset:49152
	ds_read_b128 v[190:193], v150 offset:50176
	ds_read_b128 v[200:203], v150 offset:51200
	ds_read_b128 v[204:207], v150 offset:52224
	ds_read_b128 v[208:211], v150 offset:53248
	ds_read_b128 v[212:215], v150 offset:54272
	ds_read_b128 v[220:223], v150 offset:55296
	ds_read_b128 v[230:233], v150 offset:56320
	global_load_lds_dwordx4 v[234:235], off
	s_add_i32 m0, s36, 0x2000
	s_add_u32 s34, s34, 0x160080
	v_lshl_add_u64 v[234:235], v[236:237], 0, s[2:3]
	s_addc_u32 s35, s35, 0
	s_add_i32 s36, s60, s41
	global_load_lds_dwordx4 v[234:235], off
	v_lshl_add_u64 v[234:235], s[34:35], 0, v[194:195]
	s_mov_b32 m0, s36
	s_nop 0
	global_load_lds_dwordx4 v[234:235], off
	v_lshl_add_u64 v[234:235], s[34:35], 0, v[134:135]
	s_add_i32 m0, s36, 0x2000
	s_nop 0
	global_load_lds_dwordx4 v[234:235], off
	v_lshl_add_u64 v[234:235], v[238:239], 0, s[2:3]
	s_mov_b32 m0, s47
	s_nop 0
	global_load_lds_dwordx4 v[234:235], off
	v_lshl_add_u64 v[234:235], v[240:241], 0, s[2:3]
	s_mov_b32 m0, s52
	s_nop 0
	global_load_lds_dwordx4 v[234:235], off
	s_waitcnt vmcnt(8)
	s_waitcnt lgkmcnt(0)
	s_barrier
	v_mfma_f32_16x16x32_bf16 v[62:65], v[152:155], v[186:189], v[62:65]
	v_mfma_f32_16x16x32_bf16 v[58:61], v[160:163], v[186:189], v[58:61]
	v_mfma_f32_16x16x32_bf16 v[46:49], v[152:155], v[200:203], v[46:49]
	v_mfma_f32_16x16x32_bf16 v[42:45], v[160:163], v[200:203], v[42:45]
	v_mfma_f32_16x16x32_bf16 v[30:33], v[152:155], v[208:211], v[30:33]
	v_mfma_f32_16x16x32_bf16 v[26:29], v[160:163], v[208:211], v[26:29]
	v_mfma_f32_16x16x32_bf16 v[14:17], v[152:155], v[220:223], v[14:17]
	v_mfma_f32_16x16x32_bf16 v[10:13], v[160:163], v[220:223], v[10:13]
	v_mfma_f32_16x16x32_bf16 v[62:65], v[156:159], v[190:193], v[62:65]
	v_mfma_f32_16x16x32_bf16 v[58:61], v[164:167], v[190:193], v[58:61]
	v_mfma_f32_16x16x32_bf16 v[46:49], v[156:159], v[204:207], v[46:49]
	v_mfma_f32_16x16x32_bf16 v[42:45], v[164:167], v[204:207], v[42:45]
	v_mfma_f32_16x16x32_bf16 v[30:33], v[156:159], v[212:215], v[30:33]
	v_mfma_f32_16x16x32_bf16 v[26:29], v[164:167], v[212:215], v[26:29]
	v_mfma_f32_16x16x32_bf16 v[14:17], v[156:159], v[230:233], v[14:17]
	v_mfma_f32_16x16x32_bf16 v[10:13], v[164:167], v[230:233], v[10:13]
	v_mfma_f32_16x16x32_bf16 v[54:57], v[168:171], v[186:189], v[54:57]
	v_mfma_f32_16x16x32_bf16 v[50:53], v[176:179], v[186:189], v[50:53]
	v_mfma_f32_16x16x32_bf16 v[38:41], v[168:171], v[200:203], v[38:41]
	v_mfma_f32_16x16x32_bf16 v[34:37], v[176:179], v[200:203], v[34:37]
	v_mfma_f32_16x16x32_bf16 v[22:25], v[168:171], v[208:211], v[22:25]
	v_mfma_f32_16x16x32_bf16 v[18:21], v[176:179], v[208:211], v[18:21]
	v_mfma_f32_16x16x32_bf16 v[6:9], v[168:171], v[220:223], v[6:9]
	v_mfma_f32_16x16x32_bf16 v[2:5], v[176:179], v[220:223], v[2:5]
	v_mfma_f32_16x16x32_bf16 v[54:57], v[172:175], v[190:193], v[54:57]
	v_mfma_f32_16x16x32_bf16 v[50:53], v[180:183], v[190:193], v[50:53]
	v_mfma_f32_16x16x32_bf16 v[38:41], v[172:175], v[204:207], v[38:41]
	v_mfma_f32_16x16x32_bf16 v[34:37], v[180:183], v[204:207], v[34:37]
	v_mfma_f32_16x16x32_bf16 v[22:25], v[172:175], v[212:215], v[22:25]
	v_mfma_f32_16x16x32_bf16 v[18:21], v[180:183], v[212:215], v[18:21]
	v_mfma_f32_16x16x32_bf16 v[6:9], v[172:175], v[230:233], v[6:9]
	v_mfma_f32_16x16x32_bf16 v[2:5], v[180:183], v[230:233], v[2:5]
	s_barrier
	s_add_i32 s34, s23, 2
	s_add_u32 s30, s30, 0x100
	s_addc_u32 s31, s31, 0
	v_lshl_add_u64 v[142:143], v[142:143], 0, s[62:63]
	v_lshl_add_u64 v[140:141], v[140:141], 0, s[62:63]
	s_cmp_ge_i32 s23, s21
	s_mov_b32 s23, s34
	s_cbranch_scc0 .LBB0_2328
	s_and_b64 vcc, exec, s[18:19]
	s_cbranch_vccz .LBB0_2331
	s_barrier
